# conv DPP reduction with the readlane-to-VALU pad at two wait states
# speedup vs baseline: 1.0045x; 1.0004x over previous
; __device__ __forceinline__ unsigned cvt_pk_bf16(float lo, float hi) { unsigned r; asm volatile("v_cvt_pk_bf16_f32 %0, %1, %2" : "=v"(r) : "v"(lo), "v"(hi)); return r; }
; __device__ __forceinline__ float bf_lo(unsigned w) { return __uint_as_float(w << 16); }
; __device__ __forceinline__ float bf_hi(unsigned w) { return __uint_as_float(w & 0xffff0000u); }
; __global__ void __launch_bounds__(512, 2) trunk_fwd(Args args) {
;     ...
;                 for (int rr = 0; rr < 16; ++rr) {
;                     const int r = r0 + rr;
;                     const u32x4 gb = gb_n, gu = gu_n; const f32x4 pv4 = pv_n;
;                     if (rr < 15) { gb_n = *(const u32x4*)(Z + (size_t)(r + 1) * INP + 768 + c0); gu_n = *(const u32x4*)(Z + (size_t)(r + 1) * INP + 1280 + c0);
;                                    pv_n = *(const f32x4*)(pl + (size_t)(r + 1) * PLE + lane * 4); }
;                     float cv[8], uu[8]; float ss = 0.f;
; #pragma unroll
;                     for (int i = 0; i < 4; ++i) {
;                         uu[2 * i] = bf_lo(gu[i]); uu[2 * i + 1] = bf_hi(gu[i]);
;                         cv[2 * i] = bf_lo(gb[i]) * (w0[2 * i] * uu[2 * i] + w1[2 * i] * u1[2 * i] + w2[2 * i] * u2[2 * i]);
;                         cv[2 * i + 1] = bf_hi(gb[i]) * (w0[2 * i + 1] * uu[2 * i + 1] + w1[2 * i + 1] * u1[2 * i + 1] + w2[2 * i + 1] * u2[2 * i + 1]);
;                     }
; #pragma unroll
;                     for (int i = 0; i < 8; ++i) { ss += cv[i] * cv[i]; u2[i] = u1[i]; u1[i] = uu[i]; }
;                     ss = wave_sum(ss);
;                     const float rc = rsqrtf(ss * (1.0f / 512.0f) + EPS);
;                     u32x4 oc;
; #pragma unroll
;                     for (int i = 0; i < 4; ++i) oc[i] = cvt_pk_bf16(cv[2 * i] * rc, cv[2 * i + 1] * rc);
;                     *(u32x4*)(MIX + (size_t)r * 1024 + 512 + c0) = oc;
.Lcv_taps_ok:
	v_mad_i64_i32 v[152:153], vcc, s41, v221, v[58:59]
	s_add_u32 s41, s41, 1
	global_load_dwordx4 v[2:5], v[152:153], off offset:1536
	global_load_dwordx4 v[18:21], v[152:153], off offset:2560
	v_mad_i64_i32 v[152:153], vcc, s41, v221, v[58:59]
	s_add_u32 s41, s41, 1
	global_load_dwordx4 v[6:9], v[152:153], off offset:1536
	global_load_dwordx4 v[22:25], v[152:153], off offset:2560
	v_mad_i64_i32 v[152:153], vcc, s41, v221, v[58:59]
	s_add_u32 s41, s41, 1
	global_load_dwordx4 v[10:13], v[152:153], off offset:1536
	global_load_dwordx4 v[26:29], v[152:153], off offset:2560
	v_mad_i64_i32 v[152:153], vcc, s41, v221, v[58:59]
	s_add_u32 s41, s41, 1
	global_load_dwordx4 v[14:17], v[152:153], off offset:1536
	global_load_dwordx4 v[30:33], v[152:153], off offset:2560
	s_waitcnt vmcnt(6)
	v_lshlrev_b32_e32 v188, 16, v18
	v_and_b32_e32 v189, 0xffff0000, v18
	v_lshlrev_b32_e32 v190, 16, v19
	v_and_b32_e32 v191, 0xffff0000, v19
	v_lshlrev_b32_e32 v192, 16, v20
	v_and_b32_e32 v193, 0xffff0000, v20
	v_lshlrev_b32_e32 v194, 16, v21
	v_and_b32_e32 v195, 0xffff0000, v21
	v_mul_f32_e32 v140, v164, v188
	v_mul_f32_e32 v141, v165, v189
	v_mul_f32_e32 v142, v166, v190
	v_mul_f32_e32 v143, v167, v191
	v_mul_f32_e32 v144, v168, v192
	v_mul_f32_e32 v145, v169, v193
	v_mul_f32_e32 v146, v170, v194
	v_mul_f32_e32 v147, v171, v195
	v_fmac_f32_e32 v140, v172, v204
	v_fmac_f32_e32 v141, v173, v205
	v_fmac_f32_e32 v142, v174, v206
	v_fmac_f32_e32 v143, v175, v207
	v_fmac_f32_e32 v144, v176, v208
	v_fmac_f32_e32 v145, v177, v209
	v_fmac_f32_e32 v146, v178, v210
	v_fmac_f32_e32 v147, v179, v211
	v_fmac_f32_e32 v140, v180, v196
	v_fmac_f32_e32 v141, v181, v197
	v_fmac_f32_e32 v142, v182, v198
	v_fmac_f32_e32 v143, v183, v199
	v_fmac_f32_e32 v144, v184, v200
	v_fmac_f32_e32 v145, v185, v201
	v_fmac_f32_e32 v146, v186, v202
	v_fmac_f32_e32 v147, v187, v203
	v_lshlrev_b32_e32 v150, 16, v2
	v_and_b32_e32 v151, 0xffff0000, v2
	v_mul_f32_e32 v140, v150, v140
	v_mul_f32_e32 v141, v151, v141
	v_lshlrev_b32_e32 v150, 16, v3
	v_and_b32_e32 v151, 0xffff0000, v3
	v_mul_f32_e32 v142, v150, v142
	v_mul_f32_e32 v143, v151, v143
	v_lshlrev_b32_e32 v150, 16, v4
	v_and_b32_e32 v151, 0xffff0000, v4
	v_mul_f32_e32 v144, v150, v144
	v_mul_f32_e32 v145, v151, v145
	v_lshlrev_b32_e32 v150, 16, v5
	v_and_b32_e32 v151, 0xffff0000, v5
	v_mul_f32_e32 v146, v150, v146
	v_mul_f32_e32 v147, v151, v147
	v_mul_f32_e32 v148, v140, v140
	v_fmac_f32_e32 v148, v141, v141
	v_fmac_f32_e32 v148, v142, v142
	v_fmac_f32_e32 v148, v143, v143
	v_fmac_f32_e32 v148, v144, v144
	v_fmac_f32_e32 v148, v145, v145
	v_fmac_f32_e32 v148, v146, v146
	v_fmac_f32_e32 v148, v147, v147
	v_mad_i64_i32 v[152:153], vcc, s41, v221, v[58:59]
	s_add_u32 s41, s41, 1
	global_load_dwordx4 v[2:5], v[152:153], off offset:1536
	global_load_dwordx4 v[18:21], v[152:153], off offset:2560
	s_nop 1
	v_add_f32_dpp v148, v148, v148 quad_perm:[1,0,3,2] row_mask:0xf bank_mask:0xf
	s_nop 1
	v_add_f32_dpp v148, v148, v148 quad_perm:[2,3,0,1] row_mask:0xf bank_mask:0xf
	s_nop 1
	v_add_f32_dpp v148, v148, v148 row_half_mirror row_mask:0xf bank_mask:0xf
	s_nop 1
	v_add_f32_dpp v148, v148, v148 row_mirror row_mask:0xf bank_mask:0xf
	s_nop 1
	v_add_f32_dpp v148, v148, v148 row_bcast:15 row_mask:0xa bank_mask:0xf
	s_nop 1
	v_add_f32_dpp v148, v148, v148 row_bcast:31 row_mask:0xc bank_mask:0xf
	s_nop 0
	v_readlane_b32 s0, v148, 63
	s_nop 1
	v_mov_b32_e32 v148, s0
	v_fmamk_f32 v148, v148, 0x3b000000, v162
	v_mul_f32_e32 v150, 0x4b800000, v148
	v_cmp_gt_f32_e32 vcc, s31, v148
	s_nop 1
	v_cndmask_b32_e32 v148, v148, v150, vcc
	v_rsq_f32_e32 v148, v148
	s_nop 0
	v_mul_f32_e32 v150, 0x45800000, v148
	v_cndmask_b32_e32 v149, v148, v150, vcc
	v_mul_f32_e32 v140, v149, v140
	v_mul_f32_e32 v141, v149, v141
	v_mul_f32_e32 v142, v149, v142
	v_mul_f32_e32 v143, v149, v143
	v_mul_f32_e32 v144, v149, v144
	v_mul_f32_e32 v145, v149, v145
	v_mul_f32_e32 v146, v149, v146
	v_mul_f32_e32 v147, v149, v147
	v_cvt_pk_bf16_f32 v140, v140, v141
	v_cvt_pk_bf16_f32 v141, v142, v143
	v_cvt_pk_bf16_f32 v142, v144, v145
	v_cvt_pk_bf16_f32 v143, v146, v147
	global_store_dwordx4 v[156:157], v[140:143], off
	s_waitcnt vmcnt(7)
	v_lshlrev_b32_e32 v196, 16, v22
	v_and_b32_e32 v197, 0xffff0000, v22
	v_lshlrev_b32_e32 v198, 16, v23
	v_and_b32_e32 v199, 0xffff0000, v23
	v_lshlrev_b32_e32 v200, 16, v24
	v_and_b32_e32 v201, 0xffff0000, v24
	v_lshlrev_b32_e32 v202, 16, v25
	v_and_b32_e32 v203, 0xffff0000, v25
	v_mul_f32_e32 v140, v164, v196
	v_mul_f32_e32 v141, v165, v197
	v_mul_f32_e32 v142, v166, v198
	v_mul_f32_e32 v143, v167, v199
	v_mul_f32_e32 v144, v168, v200
	v_mul_f32_e32 v145, v169, v201
	v_mul_f32_e32 v146, v170, v202
	v_mul_f32_e32 v147, v171, v203
	v_fmac_f32_e32 v140, v172, v188
	v_fmac_f32_e32 v141, v173, v189
	v_fmac_f32_e32 v142, v174, v190
	v_fmac_f32_e32 v143, v175, v191
	v_fmac_f32_e32 v144, v176, v192
	v_fmac_f32_e32 v145, v177, v193
	v_fmac_f32_e32 v146, v178, v194
	v_fmac_f32_e32 v147, v179, v195
	v_fmac_f32_e32 v140, v180, v204
	v_fmac_f32_e32 v141, v181, v205
	v_fmac_f32_e32 v142, v182, v206
	v_fmac_f32_e32 v143, v183, v207
	v_fmac_f32_e32 v144, v184, v208
	v_fmac_f32_e32 v145, v185, v209
	v_fmac_f32_e32 v146, v186, v210
	v_fmac_f32_e32 v147, v187, v211
	v_lshlrev_b32_e32 v150, 16, v6
	v_and_b32_e32 v151, 0xffff0000, v6
	v_mul_f32_e32 v140, v150, v140
	v_mul_f32_e32 v141, v151, v141
	v_lshlrev_b32_e32 v150, 16, v7
	v_and_b32_e32 v151, 0xffff0000, v7
	v_mul_f32_e32 v142, v150, v142
	v_mul_f32_e32 v143, v151, v143
	v_lshlrev_b32_e32 v150, 16, v8
	v_and_b32_e32 v151, 0xffff0000, v8
	v_mul_f32_e32 v144, v150, v144
	v_mul_f32_e32 v145, v151, v145
; __device__ __forceinline__ unsigned cvt_pk_bf16(float lo, float hi) { unsigned r; asm volatile("v_cvt_pk_bf16_f32 %0, %1, %2" : "=v"(r) : "v"(lo), "v"(hi)); return r; }
; __device__ __forceinline__ float bf_lo(unsigned w) { return __uint_as_float(w << 16); }
; __device__ __forceinline__ float bf_hi(unsigned w) { return __uint_as_float(w & 0xffff0000u); }
; __global__ void __launch_bounds__(512, 2) trunk_fwd(Args args) {
;     ...
;                 for (int rr = 0; rr < 16; ++rr) {
;                     const int r = r0 + rr;
;                     const u32x4 gb = gb_n, gu = gu_n; const f32x4 pv4 = pv_n;
;                     if (rr < 15) { gb_n = *(const u32x4*)(Z + (size_t)(r + 1) * INP + 768 + c0); gu_n = *(const u32x4*)(Z + (size_t)(r + 1) * INP + 1280 + c0);
;                                    pv_n = *(const f32x4*)(pl + (size_t)(r + 1) * PLE + lane * 4); }
;                     float cv[8], uu[8]; float ss = 0.f;
; #pragma unroll
;                     for (int i = 0; i < 4; ++i) {
;                         uu[2 * i] = bf_lo(gu[i]); uu[2 * i + 1] = bf_hi(gu[i]);
;                         cv[2 * i] = bf_lo(gb[i]) * (w0[2 * i] * uu[2 * i] + w1[2 * i] * u1[2 * i] + w2[2 * i] * u2[2 * i]);
;                         cv[2 * i + 1] = bf_hi(gb[i]) * (w0[2 * i + 1] * uu[2 * i + 1] + w1[2 * i + 1] * u1[2 * i + 1] + w2[2 * i + 1] * u2[2 * i + 1]);
;                     }
; #pragma unroll
;                     for (int i = 0; i < 8; ++i) { ss += cv[i] * cv[i]; u2[i] = u1[i]; u1[i] = uu[i]; }
;                     ss = wave_sum(ss);
;                     const float rc = rsqrtf(ss * (1.0f / 512.0f) + EPS);
;                     u32x4 oc;
; #pragma unroll
;                     for (int i = 0; i < 4; ++i) oc[i] = cvt_pk_bf16(cv[2 * i] * rc, cv[2 * i + 1] * rc);
;                     *(u32x4*)(MIX + (size_t)r * 1024 + 512 + c0) = oc;
	v_lshlrev_b32_e32 v150, 16, v9
	v_and_b32_e32 v151, 0xffff0000, v9
	v_mul_f32_e32 v146, v150, v146
	v_mul_f32_e32 v147, v151, v147
	v_mul_f32_e32 v148, v140, v140
	v_fmac_f32_e32 v148, v141, v141
	v_fmac_f32_e32 v148, v142, v142
	v_fmac_f32_e32 v148, v143, v143
	v_fmac_f32_e32 v148, v144, v144
	v_fmac_f32_e32 v148, v145, v145
	v_fmac_f32_e32 v148, v146, v146
	v_fmac_f32_e32 v148, v147, v147
	v_mad_i64_i32 v[152:153], vcc, s41, v221, v[58:59]
	s_add_u32 s41, s41, 1
	global_load_dwordx4 v[6:9], v[152:153], off offset:1536
	global_load_dwordx4 v[22:25], v[152:153], off offset:2560
	s_nop 1
	v_add_f32_dpp v148, v148, v148 quad_perm:[1,0,3,2] row_mask:0xf bank_mask:0xf
	s_nop 1
	v_add_f32_dpp v148, v148, v148 quad_perm:[2,3,0,1] row_mask:0xf bank_mask:0xf
	s_nop 1
	v_add_f32_dpp v148, v148, v148 row_half_mirror row_mask:0xf bank_mask:0xf
	s_nop 1
	v_add_f32_dpp v148, v148, v148 row_mirror row_mask:0xf bank_mask:0xf
	s_nop 1
	v_add_f32_dpp v148, v148, v148 row_bcast:15 row_mask:0xa bank_mask:0xf
	s_nop 1
	v_add_f32_dpp v148, v148, v148 row_bcast:31 row_mask:0xc bank_mask:0xf
	s_nop 0
	v_readlane_b32 s0, v148, 63
	s_nop 1
	v_mov_b32_e32 v148, s0
	v_fmamk_f32 v148, v148, 0x3b000000, v162
	v_mul_f32_e32 v150, 0x4b800000, v148
	v_cmp_gt_f32_e32 vcc, s31, v148
	s_nop 1
	v_cndmask_b32_e32 v148, v148, v150, vcc
	v_rsq_f32_e32 v148, v148
	s_nop 0
	v_mul_f32_e32 v150, 0x45800000, v148
	v_cndmask_b32_e32 v149, v148, v150, vcc
	v_mul_f32_e32 v140, v149, v140
	v_mul_f32_e32 v141, v149, v141
	v_mul_f32_e32 v142, v149, v142
	v_mul_f32_e32 v143, v149, v143
	v_mul_f32_e32 v144, v149, v144
	v_mul_f32_e32 v145, v149, v145
	v_mul_f32_e32 v146, v149, v146
	v_mul_f32_e32 v147, v149, v147
	v_cvt_pk_bf16_f32 v140, v140, v141
	v_cvt_pk_bf16_f32 v141, v142, v143
	v_cvt_pk_bf16_f32 v142, v144, v145
	v_cvt_pk_bf16_f32 v143, v146, v147
	global_store_dwordx4 v[156:157], v[140:143], off offset:2048
	v_lshl_add_u64 v[156:157], v[156:157], 0, s[20:21]
	s_waitcnt vmcnt(8)
	v_lshlrev_b32_e32 v204, 16, v26
	v_and_b32_e32 v205, 0xffff0000, v26
	v_lshlrev_b32_e32 v206, 16, v27
	v_and_b32_e32 v207, 0xffff0000, v27
	v_lshlrev_b32_e32 v208, 16, v28
	v_and_b32_e32 v209, 0xffff0000, v28
	v_lshlrev_b32_e32 v210, 16, v29
	v_and_b32_e32 v211, 0xffff0000, v29
	v_mul_f32_e32 v140, v164, v204
	v_mul_f32_e32 v141, v165, v205
	v_mul_f32_e32 v142, v166, v206
	v_mul_f32_e32 v143, v167, v207
	v_mul_f32_e32 v144, v168, v208
	v_mul_f32_e32 v145, v169, v209
	v_mul_f32_e32 v146, v170, v210
	v_mul_f32_e32 v147, v171, v211
	v_fmac_f32_e32 v140, v172, v196
	v_fmac_f32_e32 v141, v173, v197
	v_fmac_f32_e32 v142, v174, v198
	v_fmac_f32_e32 v143, v175, v199
	v_fmac_f32_e32 v144, v176, v200
	v_fmac_f32_e32 v145, v177, v201
	v_fmac_f32_e32 v146, v178, v202
	v_fmac_f32_e32 v147, v179, v203
	v_fmac_f32_e32 v140, v180, v188
	v_fmac_f32_e32 v141, v181, v189
	v_fmac_f32_e32 v142, v182, v190
	v_fmac_f32_e32 v143, v183, v191
	v_fmac_f32_e32 v144, v184, v192
	v_fmac_f32_e32 v145, v185, v193
	v_fmac_f32_e32 v146, v186, v194
	v_fmac_f32_e32 v147, v187, v195
	v_lshlrev_b32_e32 v150, 16, v10
	v_and_b32_e32 v151, 0xffff0000, v10
	v_mul_f32_e32 v140, v150, v140
	v_mul_f32_e32 v141, v151, v141
	v_lshlrev_b32_e32 v150, 16, v11
	v_and_b32_e32 v151, 0xffff0000, v11
	v_mul_f32_e32 v142, v150, v142
	v_mul_f32_e32 v143, v151, v143
	v_lshlrev_b32_e32 v150, 16, v12
	v_and_b32_e32 v151, 0xffff0000, v12
	v_mul_f32_e32 v144, v150, v144
	v_mul_f32_e32 v145, v151, v145
	v_lshlrev_b32_e32 v150, 16, v13
	v_and_b32_e32 v151, 0xffff0000, v13
	v_mul_f32_e32 v146, v150, v146
	v_mul_f32_e32 v147, v151, v147
	v_mul_f32_e32 v148, v140, v140
	v_fmac_f32_e32 v148, v141, v141
	v_fmac_f32_e32 v148, v142, v142
	v_fmac_f32_e32 v148, v143, v143
	v_fmac_f32_e32 v148, v144, v144
	v_fmac_f32_e32 v148, v145, v145
	v_fmac_f32_e32 v148, v146, v146
	v_fmac_f32_e32 v148, v147, v147
	v_mad_i64_i32 v[152:153], vcc, s41, v221, v[58:59]
	s_add_u32 s41, s41, 1
	global_load_dwordx4 v[10:13], v[152:153], off offset:1536
	global_load_dwordx4 v[26:29], v[152:153], off offset:2560
	s_nop 1
	v_add_f32_dpp v148, v148, v148 quad_perm:[1,0,3,2] row_mask:0xf bank_mask:0xf
	s_nop 1
	v_add_f32_dpp v148, v148, v148 quad_perm:[2,3,0,1] row_mask:0xf bank_mask:0xf
	s_nop 1
	v_add_f32_dpp v148, v148, v148 row_half_mirror row_mask:0xf bank_mask:0xf
	s_nop 1
	v_add_f32_dpp v148, v148, v148 row_mirror row_mask:0xf bank_mask:0xf
	s_nop 1
	v_add_f32_dpp v148, v148, v148 row_bcast:15 row_mask:0xa bank_mask:0xf
	s_nop 1
	v_add_f32_dpp v148, v148, v148 row_bcast:31 row_mask:0xc bank_mask:0xf
	s_nop 0
	v_readlane_b32 s0, v148, 63
	s_nop 1
	v_mov_b32_e32 v148, s0
	v_fmamk_f32 v148, v148, 0x3b000000, v162
	v_mul_f32_e32 v150, 0x4b800000, v148
	v_cmp_gt_f32_e32 vcc, s31, v148
	s_nop 1
	v_cndmask_b32_e32 v148, v148, v150, vcc
	v_rsq_f32_e32 v148, v148
	s_nop 0
	v_mul_f32_e32 v150, 0x45800000, v148
	v_cndmask_b32_e32 v149, v148, v150, vcc
	v_mul_f32_e32 v140, v149, v140
	v_mul_f32_e32 v141, v149, v141
	v_mul_f32_e32 v142, v149, v142
	v_mul_f32_e32 v143, v149, v143
	v_mul_f32_e32 v144, v149, v144
	v_mul_f32_e32 v145, v149, v145
	v_mul_f32_e32 v146, v149, v146
	v_mul_f32_e32 v147, v149, v147
	v_cvt_pk_bf16_f32 v140, v140, v141
	v_cvt_pk_bf16_f32 v141, v142, v143
	v_cvt_pk_bf16_f32 v142, v144, v145
	v_cvt_pk_bf16_f32 v143, v146, v147
	global_store_dwordx4 v[156:157], v[140:143], off
	s_waitcnt vmcnt(9)
; __device__ __forceinline__ unsigned cvt_pk_bf16(float lo, float hi) { unsigned r; asm volatile("v_cvt_pk_bf16_f32 %0, %1, %2" : "=v"(r) : "v"(lo), "v"(hi)); return r; }
; __device__ __forceinline__ float bf_lo(unsigned w) { return __uint_as_float(w << 16); }
; __device__ __forceinline__ float bf_hi(unsigned w) { return __uint_as_float(w & 0xffff0000u); }
; __global__ void __launch_bounds__(512, 2) trunk_fwd(Args args) {
;     ...
;                 for (int rr = 0; rr < 16; ++rr) {
;                     const int r = r0 + rr;
;                     const u32x4 gb = gb_n, gu = gu_n; const f32x4 pv4 = pv_n;
;                     if (rr < 15) { gb_n = *(const u32x4*)(Z + (size_t)(r + 1) * INP + 768 + c0); gu_n = *(const u32x4*)(Z + (size_t)(r + 1) * INP + 1280 + c0);
;                                    pv_n = *(const f32x4*)(pl + (size_t)(r + 1) * PLE + lane * 4); }
;                     float cv[8], uu[8]; float ss = 0.f;
; #pragma unroll
;                     for (int i = 0; i < 4; ++i) {
;                         uu[2 * i] = bf_lo(gu[i]); uu[2 * i + 1] = bf_hi(gu[i]);
;                         cv[2 * i] = bf_lo(gb[i]) * (w0[2 * i] * uu[2 * i] + w1[2 * i] * u1[2 * i] + w2[2 * i] * u2[2 * i]);
;                         cv[2 * i + 1] = bf_hi(gb[i]) * (w0[2 * i + 1] * uu[2 * i + 1] + w1[2 * i + 1] * u1[2 * i + 1] + w2[2 * i + 1] * u2[2 * i + 1]);
;                     }
; #pragma unroll
;                     for (int i = 0; i < 8; ++i) { ss += cv[i] * cv[i]; u2[i] = u1[i]; u1[i] = uu[i]; }
;                     ss = wave_sum(ss);
;                     const float rc = rsqrtf(ss * (1.0f / 512.0f) + EPS);
;                     u32x4 oc;
; #pragma unroll
;                     for (int i = 0; i < 4; ++i) oc[i] = cvt_pk_bf16(cv[2 * i] * rc, cv[2 * i + 1] * rc);
;                     *(u32x4*)(MIX + (size_t)r * 1024 + 512 + c0) = oc;
	v_lshlrev_b32_e32 v188, 16, v30
	v_and_b32_e32 v189, 0xffff0000, v30
	v_lshlrev_b32_e32 v190, 16, v31
	v_and_b32_e32 v191, 0xffff0000, v31
	v_lshlrev_b32_e32 v192, 16, v32
	v_and_b32_e32 v193, 0xffff0000, v32
	v_lshlrev_b32_e32 v194, 16, v33
	v_and_b32_e32 v195, 0xffff0000, v33
	v_mul_f32_e32 v140, v164, v188
	v_mul_f32_e32 v141, v165, v189
	v_mul_f32_e32 v142, v166, v190
	v_mul_f32_e32 v143, v167, v191
	v_mul_f32_e32 v144, v168, v192
	v_mul_f32_e32 v145, v169, v193
	v_mul_f32_e32 v146, v170, v194
	v_mul_f32_e32 v147, v171, v195
	v_fmac_f32_e32 v140, v172, v204
	v_fmac_f32_e32 v141, v173, v205
	v_fmac_f32_e32 v142, v174, v206
	v_fmac_f32_e32 v143, v175, v207
	v_fmac_f32_e32 v144, v176, v208
	v_fmac_f32_e32 v145, v177, v209
	v_fmac_f32_e32 v146, v178, v210
	v_fmac_f32_e32 v147, v179, v211
	v_fmac_f32_e32 v140, v180, v196
	v_fmac_f32_e32 v141, v181, v197
	v_fmac_f32_e32 v142, v182, v198
	v_fmac_f32_e32 v143, v183, v199
	v_fmac_f32_e32 v144, v184, v200
	v_fmac_f32_e32 v145, v185, v201
	v_fmac_f32_e32 v146, v186, v202
	v_fmac_f32_e32 v147, v187, v203
	v_lshlrev_b32_e32 v150, 16, v14
	v_and_b32_e32 v151, 0xffff0000, v14
	v_mul_f32_e32 v140, v150, v140
	v_mul_f32_e32 v141, v151, v141
	v_lshlrev_b32_e32 v150, 16, v15
	v_and_b32_e32 v151, 0xffff0000, v15
	v_mul_f32_e32 v142, v150, v142
	v_mul_f32_e32 v143, v151, v143
	v_lshlrev_b32_e32 v150, 16, v16
	v_and_b32_e32 v151, 0xffff0000, v16
	v_mul_f32_e32 v144, v150, v144
	v_mul_f32_e32 v145, v151, v145
	v_lshlrev_b32_e32 v150, 16, v17
	v_and_b32_e32 v151, 0xffff0000, v17
	v_mul_f32_e32 v146, v150, v146
	v_mul_f32_e32 v147, v151, v147
	v_mul_f32_e32 v148, v140, v140
	v_fmac_f32_e32 v148, v141, v141
	v_fmac_f32_e32 v148, v142, v142
	v_fmac_f32_e32 v148, v143, v143
	v_fmac_f32_e32 v148, v144, v144
	v_fmac_f32_e32 v148, v145, v145
	v_fmac_f32_e32 v148, v146, v146
	v_fmac_f32_e32 v148, v147, v147
	v_mad_i64_i32 v[152:153], vcc, s41, v221, v[58:59]
	s_add_u32 s41, s41, 1
	global_load_dwordx4 v[14:17], v[152:153], off offset:1536
	global_load_dwordx4 v[30:33], v[152:153], off offset:2560
	s_nop 1
	v_add_f32_dpp v148, v148, v148 quad_perm:[1,0,3,2] row_mask:0xf bank_mask:0xf
	s_nop 1
	v_add_f32_dpp v148, v148, v148 quad_perm:[2,3,0,1] row_mask:0xf bank_mask:0xf
	s_nop 1
	v_add_f32_dpp v148, v148, v148 row_half_mirror row_mask:0xf bank_mask:0xf
	s_nop 1
	v_add_f32_dpp v148, v148, v148 row_mirror row_mask:0xf bank_mask:0xf
	s_nop 1
	v_add_f32_dpp v148, v148, v148 row_bcast:15 row_mask:0xa bank_mask:0xf
	s_nop 1
	v_add_f32_dpp v148, v148, v148 row_bcast:31 row_mask:0xc bank_mask:0xf
	s_nop 0
	v_readlane_b32 s0, v148, 63
	s_nop 1
	v_mov_b32_e32 v148, s0
	v_fmamk_f32 v148, v148, 0x3b000000, v162
	v_mul_f32_e32 v150, 0x4b800000, v148
	v_cmp_gt_f32_e32 vcc, s31, v148
	s_nop 1
	v_cndmask_b32_e32 v148, v148, v150, vcc
	v_rsq_f32_e32 v148, v148
	s_nop 0
	v_mul_f32_e32 v150, 0x45800000, v148
	v_cndmask_b32_e32 v149, v148, v150, vcc
	v_mul_f32_e32 v140, v149, v140
	v_mul_f32_e32 v141, v149, v141
	v_mul_f32_e32 v142, v149, v142
	v_mul_f32_e32 v143, v149, v143
	v_mul_f32_e32 v144, v149, v144
	v_mul_f32_e32 v145, v149, v145
	v_mul_f32_e32 v146, v149, v146
	v_mul_f32_e32 v147, v149, v147
	v_cvt_pk_bf16_f32 v140, v140, v141
	v_cvt_pk_bf16_f32 v141, v142, v143
	v_cvt_pk_bf16_f32 v142, v144, v145
	v_cvt_pk_bf16_f32 v143, v146, v147
	global_store_dwordx4 v[156:157], v[140:143], off offset:2048
	v_lshl_add_u64 v[156:157], v[156:157], 0, s[20:21]
	s_waitcnt vmcnt(10)
	v_lshlrev_b32_e32 v196, 16, v18
	v_and_b32_e32 v197, 0xffff0000, v18
	v_lshlrev_b32_e32 v198, 16, v19
	v_and_b32_e32 v199, 0xffff0000, v19
	v_lshlrev_b32_e32 v200, 16, v20
	v_and_b32_e32 v201, 0xffff0000, v20
	v_lshlrev_b32_e32 v202, 16, v21
	v_and_b32_e32 v203, 0xffff0000, v21
	v_mul_f32_e32 v140, v164, v196
	v_mul_f32_e32 v141, v165, v197
	v_mul_f32_e32 v142, v166, v198
	v_mul_f32_e32 v143, v167, v199
	v_mul_f32_e32 v144, v168, v200
	v_mul_f32_e32 v145, v169, v201
	v_mul_f32_e32 v146, v170, v202
	v_mul_f32_e32 v147, v171, v203
	v_fmac_f32_e32 v140, v172, v188
	v_fmac_f32_e32 v141, v173, v189
	v_fmac_f32_e32 v142, v174, v190
	v_fmac_f32_e32 v143, v175, v191
	v_fmac_f32_e32 v144, v176, v192
	v_fmac_f32_e32 v145, v177, v193
	v_fmac_f32_e32 v146, v178, v194
	v_fmac_f32_e32 v147, v179, v195
	v_fmac_f32_e32 v140, v180, v204
	v_fmac_f32_e32 v141, v181, v205
	v_fmac_f32_e32 v142, v182, v206
	v_fmac_f32_e32 v143, v183, v207
	v_fmac_f32_e32 v144, v184, v208
	v_fmac_f32_e32 v145, v185, v209
	v_fmac_f32_e32 v146, v186, v210
	v_fmac_f32_e32 v147, v187, v211
	v_lshlrev_b32_e32 v150, 16, v2
	v_and_b32_e32 v151, 0xffff0000, v2
	v_mul_f32_e32 v140, v150, v140
	v_mul_f32_e32 v141, v151, v141
	v_lshlrev_b32_e32 v150, 16, v3
	v_and_b32_e32 v151, 0xffff0000, v3
	v_mul_f32_e32 v142, v150, v142
	v_mul_f32_e32 v143, v151, v143
	v_lshlrev_b32_e32 v150, 16, v4
	v_and_b32_e32 v151, 0xffff0000, v4
	v_mul_f32_e32 v144, v150, v144
	v_mul_f32_e32 v145, v151, v145
	v_lshlrev_b32_e32 v150, 16, v5
	v_and_b32_e32 v151, 0xffff0000, v5
	v_mul_f32_e32 v146, v150, v146
	v_mul_f32_e32 v147, v151, v147
	v_mul_f32_e32 v148, v140, v140
	v_fmac_f32_e32 v148, v141, v141
	v_fmac_f32_e32 v148, v142, v142
	v_fmac_f32_e32 v148, v143, v143
	v_fmac_f32_e32 v148, v144, v144
	v_fmac_f32_e32 v148, v145, v145
	v_fmac_f32_e32 v148, v146, v146
	v_fmac_f32_e32 v148, v147, v147
	v_mad_i64_i32 v[152:153], vcc, s41, v221, v[58:59]
	s_add_u32 s41, s41, 1
	global_load_dwordx4 v[2:5], v[152:153], off offset:1536
	global_load_dwordx4 v[18:21], v[152:153], off offset:2560
	s_nop 1
	v_add_f32_dpp v148, v148, v148 quad_perm:[1,0,3,2] row_mask:0xf bank_mask:0xf
	s_nop 1
	v_add_f32_dpp v148, v148, v148 quad_perm:[2,3,0,1] row_mask:0xf bank_mask:0xf
	s_nop 1
	v_add_f32_dpp v148, v148, v148 row_half_mirror row_mask:0xf bank_mask:0xf
	s_nop 1
	v_add_f32_dpp v148, v148, v148 row_mirror row_mask:0xf bank_mask:0xf
	s_nop 1
	v_add_f32_dpp v148, v148, v148 row_bcast:15 row_mask:0xa bank_mask:0xf
	s_nop 1
	v_add_f32_dpp v148, v148, v148 row_bcast:31 row_mask:0xc bank_mask:0xf
	s_nop 0
	v_readlane_b32 s0, v148, 63
	s_nop 1
	v_mov_b32_e32 v148, s0
	v_fmamk_f32 v148, v148, 0x3b000000, v162
	v_mul_f32_e32 v150, 0x4b800000, v148
	v_cmp_gt_f32_e32 vcc, s31, v148
	s_nop 1
	v_cndmask_b32_e32 v148, v148, v150, vcc
	v_rsq_f32_e32 v148, v148
	s_nop 0
	v_mul_f32_e32 v150, 0x45800000, v148
	v_cndmask_b32_e32 v149, v148, v150, vcc
	v_mul_f32_e32 v140, v149, v140
	v_mul_f32_e32 v141, v149, v141
	v_mul_f32_e32 v142, v149, v142
	v_mul_f32_e32 v143, v149, v143
	v_mul_f32_e32 v144, v149, v144
	v_mul_f32_e32 v145, v149, v145
	v_mul_f32_e32 v146, v149, v146
	v_mul_f32_e32 v147, v149, v147
	v_cvt_pk_bf16_f32 v140, v140, v141
	v_cvt_pk_bf16_f32 v141, v142, v143
	v_cvt_pk_bf16_f32 v142, v144, v145
	v_cvt_pk_bf16_f32 v143, v146, v147
	global_store_dwordx4 v[156:157], v[140:143], off
	s_waitcnt vmcnt(10)
; __device__ __forceinline__ unsigned cvt_pk_bf16(float lo, float hi) { unsigned r; asm volatile("v_cvt_pk_bf16_f32 %0, %1, %2" : "=v"(r) : "v"(lo), "v"(hi)); return r; }
; __device__ __forceinline__ float bf_lo(unsigned w) { return __uint_as_float(w << 16); }
; __device__ __forceinline__ float bf_hi(unsigned w) { return __uint_as_float(w & 0xffff0000u); }
; __global__ void __launch_bounds__(512, 2) trunk_fwd(Args args) {
;     ...
;                 for (int rr = 0; rr < 16; ++rr) {
;                     const int r = r0 + rr;
;                     const u32x4 gb = gb_n, gu = gu_n; const f32x4 pv4 = pv_n;
;                     if (rr < 15) { gb_n = *(const u32x4*)(Z + (size_t)(r + 1) * INP + 768 + c0); gu_n = *(const u32x4*)(Z + (size_t)(r + 1) * INP + 1280 + c0);
;                                    pv_n = *(const f32x4*)(pl + (size_t)(r + 1) * PLE + lane * 4); }
;                     float cv[8], uu[8]; float ss = 0.f;
; #pragma unroll
;                     for (int i = 0; i < 4; ++i) {
;                         uu[2 * i] = bf_lo(gu[i]); uu[2 * i + 1] = bf_hi(gu[i]);
;                         cv[2 * i] = bf_lo(gb[i]) * (w0[2 * i] * uu[2 * i] + w1[2 * i] * u1[2 * i] + w2[2 * i] * u2[2 * i]);
;                         cv[2 * i + 1] = bf_hi(gb[i]) * (w0[2 * i + 1] * uu[2 * i + 1] + w1[2 * i + 1] * u1[2 * i + 1] + w2[2 * i + 1] * u2[2 * i + 1]);
;                     }
; #pragma unroll
;                     for (int i = 0; i < 8; ++i) { ss += cv[i] * cv[i]; u2[i] = u1[i]; u1[i] = uu[i]; }
;                     ss = wave_sum(ss);
;                     const float rc = rsqrtf(ss * (1.0f / 512.0f) + EPS);
;                     u32x4 oc;
; #pragma unroll
;                     for (int i = 0; i < 4; ++i) oc[i] = cvt_pk_bf16(cv[2 * i] * rc, cv[2 * i + 1] * rc);
;                     *(u32x4*)(MIX + (size_t)r * 1024 + 512 + c0) = oc;
	v_lshlrev_b32_e32 v204, 16, v22
	v_and_b32_e32 v205, 0xffff0000, v22
	v_lshlrev_b32_e32 v206, 16, v23
	v_and_b32_e32 v207, 0xffff0000, v23
	v_lshlrev_b32_e32 v208, 16, v24
	v_and_b32_e32 v209, 0xffff0000, v24
	v_lshlrev_b32_e32 v210, 16, v25
	v_and_b32_e32 v211, 0xffff0000, v25
	v_mul_f32_e32 v140, v164, v204
	v_mul_f32_e32 v141, v165, v205
	v_mul_f32_e32 v142, v166, v206
	v_mul_f32_e32 v143, v167, v207
	v_mul_f32_e32 v144, v168, v208
	v_mul_f32_e32 v145, v169, v209
	v_mul_f32_e32 v146, v170, v210
	v_mul_f32_e32 v147, v171, v211
	v_fmac_f32_e32 v140, v172, v196
	v_fmac_f32_e32 v141, v173, v197
	v_fmac_f32_e32 v142, v174, v198
	v_fmac_f32_e32 v143, v175, v199
	v_fmac_f32_e32 v144, v176, v200
	v_fmac_f32_e32 v145, v177, v201
	v_fmac_f32_e32 v146, v178, v202
	v_fmac_f32_e32 v147, v179, v203
	v_fmac_f32_e32 v140, v180, v188
	v_fmac_f32_e32 v141, v181, v189
	v_fmac_f32_e32 v142, v182, v190
	v_fmac_f32_e32 v143, v183, v191
	v_fmac_f32_e32 v144, v184, v192
	v_fmac_f32_e32 v145, v185, v193
	v_fmac_f32_e32 v146, v186, v194
	v_fmac_f32_e32 v147, v187, v195
	v_lshlrev_b32_e32 v150, 16, v6
	v_and_b32_e32 v151, 0xffff0000, v6
	v_mul_f32_e32 v140, v150, v140
	v_mul_f32_e32 v141, v151, v141
	v_lshlrev_b32_e32 v150, 16, v7
	v_and_b32_e32 v151, 0xffff0000, v7
	v_mul_f32_e32 v142, v150, v142
	v_mul_f32_e32 v143, v151, v143
	v_lshlrev_b32_e32 v150, 16, v8
	v_and_b32_e32 v151, 0xffff0000, v8
	v_mul_f32_e32 v144, v150, v144
	v_mul_f32_e32 v145, v151, v145
	v_lshlrev_b32_e32 v150, 16, v9
	v_and_b32_e32 v151, 0xffff0000, v9
	v_mul_f32_e32 v146, v150, v146
	v_mul_f32_e32 v147, v151, v147
	v_mul_f32_e32 v148, v140, v140
	v_fmac_f32_e32 v148, v141, v141
	v_fmac_f32_e32 v148, v142, v142
	v_fmac_f32_e32 v148, v143, v143
	v_fmac_f32_e32 v148, v144, v144
	v_fmac_f32_e32 v148, v145, v145
	v_fmac_f32_e32 v148, v146, v146
	v_fmac_f32_e32 v148, v147, v147
	v_mad_i64_i32 v[152:153], vcc, s41, v221, v[58:59]
	s_add_u32 s41, s41, 1
	global_load_dwordx4 v[6:9], v[152:153], off offset:1536
	global_load_dwordx4 v[22:25], v[152:153], off offset:2560
	s_nop 1
	v_add_f32_dpp v148, v148, v148 quad_perm:[1,0,3,2] row_mask:0xf bank_mask:0xf
	s_nop 1
	v_add_f32_dpp v148, v148, v148 quad_perm:[2,3,0,1] row_mask:0xf bank_mask:0xf
	s_nop 1
	v_add_f32_dpp v148, v148, v148 row_half_mirror row_mask:0xf bank_mask:0xf
	s_nop 1
	v_add_f32_dpp v148, v148, v148 row_mirror row_mask:0xf bank_mask:0xf
	s_nop 1
	v_add_f32_dpp v148, v148, v148 row_bcast:15 row_mask:0xa bank_mask:0xf
	s_nop 1
	v_add_f32_dpp v148, v148, v148 row_bcast:31 row_mask:0xc bank_mask:0xf
	s_nop 0
	v_readlane_b32 s0, v148, 63
	s_nop 1
	v_mov_b32_e32 v148, s0
	v_fmamk_f32 v148, v148, 0x3b000000, v162
	v_mul_f32_e32 v150, 0x4b800000, v148
	v_cmp_gt_f32_e32 vcc, s31, v148
	s_nop 1
	v_cndmask_b32_e32 v148, v148, v150, vcc
	v_rsq_f32_e32 v148, v148
	s_nop 0
	v_mul_f32_e32 v150, 0x45800000, v148
	v_cndmask_b32_e32 v149, v148, v150, vcc
	v_mul_f32_e32 v140, v149, v140
	v_mul_f32_e32 v141, v149, v141
	v_mul_f32_e32 v142, v149, v142
	v_mul_f32_e32 v143, v149, v143
	v_mul_f32_e32 v144, v149, v144
	v_mul_f32_e32 v145, v149, v145
	v_mul_f32_e32 v146, v149, v146
	v_mul_f32_e32 v147, v149, v147
	v_cvt_pk_bf16_f32 v140, v140, v141
	v_cvt_pk_bf16_f32 v141, v142, v143
	v_cvt_pk_bf16_f32 v142, v144, v145
	v_cvt_pk_bf16_f32 v143, v146, v147
	global_store_dwordx4 v[156:157], v[140:143], off offset:2048
	v_lshl_add_u64 v[156:157], v[156:157], 0, s[20:21]
	s_waitcnt vmcnt(10)
	v_lshlrev_b32_e32 v188, 16, v26
	v_and_b32_e32 v189, 0xffff0000, v26
	v_lshlrev_b32_e32 v190, 16, v27
	v_and_b32_e32 v191, 0xffff0000, v27
	v_lshlrev_b32_e32 v192, 16, v28
	v_and_b32_e32 v193, 0xffff0000, v28
	v_lshlrev_b32_e32 v194, 16, v29
	v_and_b32_e32 v195, 0xffff0000, v29
	v_mul_f32_e32 v140, v164, v188
	v_mul_f32_e32 v141, v165, v189
	v_mul_f32_e32 v142, v166, v190
	v_mul_f32_e32 v143, v167, v191
	v_mul_f32_e32 v144, v168, v192
	v_mul_f32_e32 v145, v169, v193
	v_mul_f32_e32 v146, v170, v194
	v_mul_f32_e32 v147, v171, v195
	v_fmac_f32_e32 v140, v172, v204
	v_fmac_f32_e32 v141, v173, v205
	v_fmac_f32_e32 v142, v174, v206
	v_fmac_f32_e32 v143, v175, v207
	v_fmac_f32_e32 v144, v176, v208
	v_fmac_f32_e32 v145, v177, v209
	v_fmac_f32_e32 v146, v178, v210
	v_fmac_f32_e32 v147, v179, v211
	v_fmac_f32_e32 v140, v180, v196
	v_fmac_f32_e32 v141, v181, v197
	v_fmac_f32_e32 v142, v182, v198
	v_fmac_f32_e32 v143, v183, v199
	v_fmac_f32_e32 v144, v184, v200
	v_fmac_f32_e32 v145, v185, v201
	v_fmac_f32_e32 v146, v186, v202
	v_fmac_f32_e32 v147, v187, v203
	v_lshlrev_b32_e32 v150, 16, v10
	v_and_b32_e32 v151, 0xffff0000, v10
	v_mul_f32_e32 v140, v150, v140
	v_mul_f32_e32 v141, v151, v141
	v_lshlrev_b32_e32 v150, 16, v11
	v_and_b32_e32 v151, 0xffff0000, v11
	v_mul_f32_e32 v142, v150, v142
	v_mul_f32_e32 v143, v151, v143
	v_lshlrev_b32_e32 v150, 16, v12
	v_and_b32_e32 v151, 0xffff0000, v12
	v_mul_f32_e32 v144, v150, v144
	v_mul_f32_e32 v145, v151, v145
	v_lshlrev_b32_e32 v150, 16, v13
	v_and_b32_e32 v151, 0xffff0000, v13
	v_mul_f32_e32 v146, v150, v146
	v_mul_f32_e32 v147, v151, v147
	v_mul_f32_e32 v148, v140, v140
	v_fmac_f32_e32 v148, v141, v141
	v_fmac_f32_e32 v148, v142, v142
	v_fmac_f32_e32 v148, v143, v143
	v_fmac_f32_e32 v148, v144, v144
	v_fmac_f32_e32 v148, v145, v145
	v_fmac_f32_e32 v148, v146, v146
	v_fmac_f32_e32 v148, v147, v147
	v_mad_i64_i32 v[152:153], vcc, s41, v221, v[58:59]
	s_add_u32 s41, s41, 1
	global_load_dwordx4 v[10:13], v[152:153], off offset:1536
	global_load_dwordx4 v[26:29], v[152:153], off offset:2560
	s_nop 1
	v_add_f32_dpp v148, v148, v148 quad_perm:[1,0,3,2] row_mask:0xf bank_mask:0xf
	s_nop 1
	v_add_f32_dpp v148, v148, v148 quad_perm:[2,3,0,1] row_mask:0xf bank_mask:0xf
	s_nop 1
	v_add_f32_dpp v148, v148, v148 row_half_mirror row_mask:0xf bank_mask:0xf
	s_nop 1
	v_add_f32_dpp v148, v148, v148 row_mirror row_mask:0xf bank_mask:0xf
	s_nop 1
	v_add_f32_dpp v148, v148, v148 row_bcast:15 row_mask:0xa bank_mask:0xf
	s_nop 1
	v_add_f32_dpp v148, v148, v148 row_bcast:31 row_mask:0xc bank_mask:0xf
	s_nop 0
	v_readlane_b32 s0, v148, 63
	s_nop 1
	v_mov_b32_e32 v148, s0
	v_fmamk_f32 v148, v148, 0x3b000000, v162
	v_mul_f32_e32 v150, 0x4b800000, v148
	v_cmp_gt_f32_e32 vcc, s31, v148
	s_nop 1
	v_cndmask_b32_e32 v148, v148, v150, vcc
	v_rsq_f32_e32 v148, v148
	s_nop 0
	v_mul_f32_e32 v150, 0x45800000, v148
	v_cndmask_b32_e32 v149, v148, v150, vcc
	v_mul_f32_e32 v140, v149, v140
	v_mul_f32_e32 v141, v149, v141
	v_mul_f32_e32 v142, v149, v142
	v_mul_f32_e32 v143, v149, v143
	v_mul_f32_e32 v144, v149, v144
	v_mul_f32_e32 v145, v149, v145
	v_mul_f32_e32 v146, v149, v146
	v_mul_f32_e32 v147, v149, v147
	v_cvt_pk_bf16_f32 v140, v140, v141
	v_cvt_pk_bf16_f32 v141, v142, v143
	v_cvt_pk_bf16_f32 v142, v144, v145
	v_cvt_pk_bf16_f32 v143, v146, v147
	global_store_dwordx4 v[156:157], v[140:143], off
	s_waitcnt vmcnt(10)
; __device__ __forceinline__ unsigned cvt_pk_bf16(float lo, float hi) { unsigned r; asm volatile("v_cvt_pk_bf16_f32 %0, %1, %2" : "=v"(r) : "v"(lo), "v"(hi)); return r; }
; __device__ __forceinline__ float bf_lo(unsigned w) { return __uint_as_float(w << 16); }
; __device__ __forceinline__ float bf_hi(unsigned w) { return __uint_as_float(w & 0xffff0000u); }
; __global__ void __launch_bounds__(512, 2) trunk_fwd(Args args) {
;     ...
;                 for (int rr = 0; rr < 16; ++rr) {
;                     const int r = r0 + rr;
;                     const u32x4 gb = gb_n, gu = gu_n; const f32x4 pv4 = pv_n;
;                     if (rr < 15) { gb_n = *(const u32x4*)(Z + (size_t)(r + 1) * INP + 768 + c0); gu_n = *(const u32x4*)(Z + (size_t)(r + 1) * INP + 1280 + c0);
;                                    pv_n = *(const f32x4*)(pl + (size_t)(r + 1) * PLE + lane * 4); }
;                     float cv[8], uu[8]; float ss = 0.f;
; #pragma unroll
;                     for (int i = 0; i < 4; ++i) {
;                         uu[2 * i] = bf_lo(gu[i]); uu[2 * i + 1] = bf_hi(gu[i]);
;                         cv[2 * i] = bf_lo(gb[i]) * (w0[2 * i] * uu[2 * i] + w1[2 * i] * u1[2 * i] + w2[2 * i] * u2[2 * i]);
;                         cv[2 * i + 1] = bf_hi(gb[i]) * (w0[2 * i + 1] * uu[2 * i + 1] + w1[2 * i + 1] * u1[2 * i + 1] + w2[2 * i + 1] * u2[2 * i + 1]);
;                     }
; #pragma unroll
;                     for (int i = 0; i < 8; ++i) { ss += cv[i] * cv[i]; u2[i] = u1[i]; u1[i] = uu[i]; }
;                     ss = wave_sum(ss);
;                     const float rc = rsqrtf(ss * (1.0f / 512.0f) + EPS);
;                     u32x4 oc;
; #pragma unroll
;                     for (int i = 0; i < 4; ++i) oc[i] = cvt_pk_bf16(cv[2 * i] * rc, cv[2 * i + 1] * rc);
;                     *(u32x4*)(MIX + (size_t)r * 1024 + 512 + c0) = oc;
	v_lshlrev_b32_e32 v196, 16, v30
	v_and_b32_e32 v197, 0xffff0000, v30
	v_lshlrev_b32_e32 v198, 16, v31
	v_and_b32_e32 v199, 0xffff0000, v31
	v_lshlrev_b32_e32 v200, 16, v32
	v_and_b32_e32 v201, 0xffff0000, v32
	v_lshlrev_b32_e32 v202, 16, v33
	v_and_b32_e32 v203, 0xffff0000, v33
	v_mul_f32_e32 v140, v164, v196
	v_mul_f32_e32 v141, v165, v197
	v_mul_f32_e32 v142, v166, v198
	v_mul_f32_e32 v143, v167, v199
	v_mul_f32_e32 v144, v168, v200
	v_mul_f32_e32 v145, v169, v201
	v_mul_f32_e32 v146, v170, v202
	v_mul_f32_e32 v147, v171, v203
	v_fmac_f32_e32 v140, v172, v188
	v_fmac_f32_e32 v141, v173, v189
	v_fmac_f32_e32 v142, v174, v190
	v_fmac_f32_e32 v143, v175, v191
	v_fmac_f32_e32 v144, v176, v192
	v_fmac_f32_e32 v145, v177, v193
	v_fmac_f32_e32 v146, v178, v194
	v_fmac_f32_e32 v147, v179, v195
	v_fmac_f32_e32 v140, v180, v204
	v_fmac_f32_e32 v141, v181, v205
	v_fmac_f32_e32 v142, v182, v206
	v_fmac_f32_e32 v143, v183, v207
	v_fmac_f32_e32 v144, v184, v208
	v_fmac_f32_e32 v145, v185, v209
	v_fmac_f32_e32 v146, v186, v210
	v_fmac_f32_e32 v147, v187, v211
	v_lshlrev_b32_e32 v150, 16, v14
	v_and_b32_e32 v151, 0xffff0000, v14
	v_mul_f32_e32 v140, v150, v140
	v_mul_f32_e32 v141, v151, v141
	v_lshlrev_b32_e32 v150, 16, v15
	v_and_b32_e32 v151, 0xffff0000, v15
	v_mul_f32_e32 v142, v150, v142
	v_mul_f32_e32 v143, v151, v143
	v_lshlrev_b32_e32 v150, 16, v16
	v_and_b32_e32 v151, 0xffff0000, v16
	v_mul_f32_e32 v144, v150, v144
	v_mul_f32_e32 v145, v151, v145
	v_lshlrev_b32_e32 v150, 16, v17
	v_and_b32_e32 v151, 0xffff0000, v17
	v_mul_f32_e32 v146, v150, v146
	v_mul_f32_e32 v147, v151, v147
	v_mul_f32_e32 v148, v140, v140
	v_fmac_f32_e32 v148, v141, v141
	v_fmac_f32_e32 v148, v142, v142
	v_fmac_f32_e32 v148, v143, v143
	v_fmac_f32_e32 v148, v144, v144
	v_fmac_f32_e32 v148, v145, v145
	v_fmac_f32_e32 v148, v146, v146
	v_fmac_f32_e32 v148, v147, v147
	v_mad_i64_i32 v[152:153], vcc, s41, v221, v[58:59]
	s_add_u32 s41, s41, 1
	global_load_dwordx4 v[14:17], v[152:153], off offset:1536
	global_load_dwordx4 v[30:33], v[152:153], off offset:2560
	s_nop 1
	v_add_f32_dpp v148, v148, v148 quad_perm:[1,0,3,2] row_mask:0xf bank_mask:0xf
	s_nop 1
	v_add_f32_dpp v148, v148, v148 quad_perm:[2,3,0,1] row_mask:0xf bank_mask:0xf
	s_nop 1
	v_add_f32_dpp v148, v148, v148 row_half_mirror row_mask:0xf bank_mask:0xf
	s_nop 1
	v_add_f32_dpp v148, v148, v148 row_mirror row_mask:0xf bank_mask:0xf
	s_nop 1
	v_add_f32_dpp v148, v148, v148 row_bcast:15 row_mask:0xa bank_mask:0xf
	s_nop 1
	v_add_f32_dpp v148, v148, v148 row_bcast:31 row_mask:0xc bank_mask:0xf
	s_nop 0
	v_readlane_b32 s0, v148, 63
	s_nop 1
	v_mov_b32_e32 v148, s0
	v_fmamk_f32 v148, v148, 0x3b000000, v162
	v_mul_f32_e32 v150, 0x4b800000, v148
	v_cmp_gt_f32_e32 vcc, s31, v148
	s_nop 1
	v_cndmask_b32_e32 v148, v148, v150, vcc
	v_rsq_f32_e32 v148, v148
	s_nop 0
	v_mul_f32_e32 v150, 0x45800000, v148
	v_cndmask_b32_e32 v149, v148, v150, vcc
	v_mul_f32_e32 v140, v149, v140
	v_mul_f32_e32 v141, v149, v141
	v_mul_f32_e32 v142, v149, v142
	v_mul_f32_e32 v143, v149, v143
	v_mul_f32_e32 v144, v149, v144
	v_mul_f32_e32 v145, v149, v145
	v_mul_f32_e32 v146, v149, v146
	v_mul_f32_e32 v147, v149, v147
	v_cvt_pk_bf16_f32 v140, v140, v141
	v_cvt_pk_bf16_f32 v141, v142, v143
	v_cvt_pk_bf16_f32 v142, v144, v145
	v_cvt_pk_bf16_f32 v143, v146, v147
	global_store_dwordx4 v[156:157], v[140:143], off offset:2048
	v_lshl_add_u64 v[156:157], v[156:157], 0, s[20:21]
	s_waitcnt vmcnt(10)
	v_lshlrev_b32_e32 v204, 16, v18
	v_and_b32_e32 v205, 0xffff0000, v18
	v_lshlrev_b32_e32 v206, 16, v19
	v_and_b32_e32 v207, 0xffff0000, v19
	v_lshlrev_b32_e32 v208, 16, v20
	v_and_b32_e32 v209, 0xffff0000, v20
	v_lshlrev_b32_e32 v210, 16, v21
	v_and_b32_e32 v211, 0xffff0000, v21
	v_mul_f32_e32 v140, v164, v204
	v_mul_f32_e32 v141, v165, v205
	v_mul_f32_e32 v142, v166, v206
	v_mul_f32_e32 v143, v167, v207
	v_mul_f32_e32 v144, v168, v208
	v_mul_f32_e32 v145, v169, v209
	v_mul_f32_e32 v146, v170, v210
	v_mul_f32_e32 v147, v171, v211
	v_fmac_f32_e32 v140, v172, v196
	v_fmac_f32_e32 v141, v173, v197
	v_fmac_f32_e32 v142, v174, v198
	v_fmac_f32_e32 v143, v175, v199
	v_fmac_f32_e32 v144, v176, v200
	v_fmac_f32_e32 v145, v177, v201
	v_fmac_f32_e32 v146, v178, v202
	v_fmac_f32_e32 v147, v179, v203
	v_fmac_f32_e32 v140, v180, v188
	v_fmac_f32_e32 v141, v181, v189
	v_fmac_f32_e32 v142, v182, v190
	v_fmac_f32_e32 v143, v183, v191
	v_fmac_f32_e32 v144, v184, v192
	v_fmac_f32_e32 v145, v185, v193
	v_fmac_f32_e32 v146, v186, v194
	v_fmac_f32_e32 v147, v187, v195
	v_lshlrev_b32_e32 v150, 16, v2
	v_and_b32_e32 v151, 0xffff0000, v2
	v_mul_f32_e32 v140, v150, v140
	v_mul_f32_e32 v141, v151, v141
	v_lshlrev_b32_e32 v150, 16, v3
	v_and_b32_e32 v151, 0xffff0000, v3
	v_mul_f32_e32 v142, v150, v142
	v_mul_f32_e32 v143, v151, v143
	v_lshlrev_b32_e32 v150, 16, v4
	v_and_b32_e32 v151, 0xffff0000, v4
	v_mul_f32_e32 v144, v150, v144
	v_mul_f32_e32 v145, v151, v145
	v_lshlrev_b32_e32 v150, 16, v5
	v_and_b32_e32 v151, 0xffff0000, v5
	v_mul_f32_e32 v146, v150, v146
	v_mul_f32_e32 v147, v151, v147
	v_mul_f32_e32 v148, v140, v140
	v_fmac_f32_e32 v148, v141, v141
	v_fmac_f32_e32 v148, v142, v142
	v_fmac_f32_e32 v148, v143, v143
	v_fmac_f32_e32 v148, v144, v144
	v_fmac_f32_e32 v148, v145, v145
	v_fmac_f32_e32 v148, v146, v146
	v_fmac_f32_e32 v148, v147, v147
	v_mad_i64_i32 v[152:153], vcc, s41, v221, v[58:59]
	s_add_u32 s41, s41, 1
	global_load_dwordx4 v[2:5], v[152:153], off offset:1536
	global_load_dwordx4 v[18:21], v[152:153], off offset:2560
	s_nop 1
	v_add_f32_dpp v148, v148, v148 quad_perm:[1,0,3,2] row_mask:0xf bank_mask:0xf
	s_nop 1
	v_add_f32_dpp v148, v148, v148 quad_perm:[2,3,0,1] row_mask:0xf bank_mask:0xf
	s_nop 1
	v_add_f32_dpp v148, v148, v148 row_half_mirror row_mask:0xf bank_mask:0xf
	s_nop 1
	v_add_f32_dpp v148, v148, v148 row_mirror row_mask:0xf bank_mask:0xf
	s_nop 1
	v_add_f32_dpp v148, v148, v148 row_bcast:15 row_mask:0xa bank_mask:0xf
	s_nop 1
	v_add_f32_dpp v148, v148, v148 row_bcast:31 row_mask:0xc bank_mask:0xf
	s_nop 0
	v_readlane_b32 s0, v148, 63
	s_nop 1
	v_mov_b32_e32 v148, s0
	v_fmamk_f32 v148, v148, 0x3b000000, v162
	v_mul_f32_e32 v150, 0x4b800000, v148
	v_cmp_gt_f32_e32 vcc, s31, v148
	s_nop 1
	v_cndmask_b32_e32 v148, v148, v150, vcc
	v_rsq_f32_e32 v148, v148
	s_nop 0
	v_mul_f32_e32 v150, 0x45800000, v148
	v_cndmask_b32_e32 v149, v148, v150, vcc
	v_mul_f32_e32 v140, v149, v140
	v_mul_f32_e32 v141, v149, v141
	v_mul_f32_e32 v142, v149, v142
	v_mul_f32_e32 v143, v149, v143
	v_mul_f32_e32 v144, v149, v144
	v_mul_f32_e32 v145, v149, v145
	v_mul_f32_e32 v146, v149, v146
	v_mul_f32_e32 v147, v149, v147
	v_cvt_pk_bf16_f32 v140, v140, v141
	v_cvt_pk_bf16_f32 v141, v142, v143
	v_cvt_pk_bf16_f32 v142, v144, v145
	v_cvt_pk_bf16_f32 v143, v146, v147
	global_store_dwordx4 v[156:157], v[140:143], off
	s_waitcnt vmcnt(10)
; __device__ __forceinline__ unsigned cvt_pk_bf16(float lo, float hi) { unsigned r; asm volatile("v_cvt_pk_bf16_f32 %0, %1, %2" : "=v"(r) : "v"(lo), "v"(hi)); return r; }
; __device__ __forceinline__ float bf_lo(unsigned w) { return __uint_as_float(w << 16); }
; __device__ __forceinline__ float bf_hi(unsigned w) { return __uint_as_float(w & 0xffff0000u); }
; __global__ void __launch_bounds__(512, 2) trunk_fwd(Args args) {
;     ...
;                 for (int rr = 0; rr < 16; ++rr) {
;                     const int r = r0 + rr;
;                     const u32x4 gb = gb_n, gu = gu_n; const f32x4 pv4 = pv_n;
;                     if (rr < 15) { gb_n = *(const u32x4*)(Z + (size_t)(r + 1) * INP + 768 + c0); gu_n = *(const u32x4*)(Z + (size_t)(r + 1) * INP + 1280 + c0);
;                                    pv_n = *(const f32x4*)(pl + (size_t)(r + 1) * PLE + lane * 4); }
;                     float cv[8], uu[8]; float ss = 0.f;
; #pragma unroll
;                     for (int i = 0; i < 4; ++i) {
;                         uu[2 * i] = bf_lo(gu[i]); uu[2 * i + 1] = bf_hi(gu[i]);
;                         cv[2 * i] = bf_lo(gb[i]) * (w0[2 * i] * uu[2 * i] + w1[2 * i] * u1[2 * i] + w2[2 * i] * u2[2 * i]);
;                         cv[2 * i + 1] = bf_hi(gb[i]) * (w0[2 * i + 1] * uu[2 * i + 1] + w1[2 * i + 1] * u1[2 * i + 1] + w2[2 * i + 1] * u2[2 * i + 1]);
;                     }
; #pragma unroll
;                     for (int i = 0; i < 8; ++i) { ss += cv[i] * cv[i]; u2[i] = u1[i]; u1[i] = uu[i]; }
;                     ss = wave_sum(ss);
;                     const float rc = rsqrtf(ss * (1.0f / 512.0f) + EPS);
;                     u32x4 oc;
; #pragma unroll
;                     for (int i = 0; i < 4; ++i) oc[i] = cvt_pk_bf16(cv[2 * i] * rc, cv[2 * i + 1] * rc);
;                     *(u32x4*)(MIX + (size_t)r * 1024 + 512 + c0) = oc;
	v_lshlrev_b32_e32 v188, 16, v22
	v_and_b32_e32 v189, 0xffff0000, v22
	v_lshlrev_b32_e32 v190, 16, v23
	v_and_b32_e32 v191, 0xffff0000, v23
	v_lshlrev_b32_e32 v192, 16, v24
	v_and_b32_e32 v193, 0xffff0000, v24
	v_lshlrev_b32_e32 v194, 16, v25
	v_and_b32_e32 v195, 0xffff0000, v25
	v_mul_f32_e32 v140, v164, v188
	v_mul_f32_e32 v141, v165, v189
	v_mul_f32_e32 v142, v166, v190
	v_mul_f32_e32 v143, v167, v191
	v_mul_f32_e32 v144, v168, v192
	v_mul_f32_e32 v145, v169, v193
	v_mul_f32_e32 v146, v170, v194
	v_mul_f32_e32 v147, v171, v195
	v_fmac_f32_e32 v140, v172, v204
	v_fmac_f32_e32 v141, v173, v205
	v_fmac_f32_e32 v142, v174, v206
	v_fmac_f32_e32 v143, v175, v207
	v_fmac_f32_e32 v144, v176, v208
	v_fmac_f32_e32 v145, v177, v209
	v_fmac_f32_e32 v146, v178, v210
	v_fmac_f32_e32 v147, v179, v211
	v_fmac_f32_e32 v140, v180, v196
	v_fmac_f32_e32 v141, v181, v197
	v_fmac_f32_e32 v142, v182, v198
	v_fmac_f32_e32 v143, v183, v199
	v_fmac_f32_e32 v144, v184, v200
	v_fmac_f32_e32 v145, v185, v201
	v_fmac_f32_e32 v146, v186, v202
	v_fmac_f32_e32 v147, v187, v203
	v_lshlrev_b32_e32 v150, 16, v6
	v_and_b32_e32 v151, 0xffff0000, v6
	v_mul_f32_e32 v140, v150, v140
	v_mul_f32_e32 v141, v151, v141
	v_lshlrev_b32_e32 v150, 16, v7
	v_and_b32_e32 v151, 0xffff0000, v7
	v_mul_f32_e32 v142, v150, v142
	v_mul_f32_e32 v143, v151, v143
	v_lshlrev_b32_e32 v150, 16, v8
	v_and_b32_e32 v151, 0xffff0000, v8
	v_mul_f32_e32 v144, v150, v144
	v_mul_f32_e32 v145, v151, v145
	v_lshlrev_b32_e32 v150, 16, v9
	v_and_b32_e32 v151, 0xffff0000, v9
	v_mul_f32_e32 v146, v150, v146
	v_mul_f32_e32 v147, v151, v147
	v_mul_f32_e32 v148, v140, v140
	v_fmac_f32_e32 v148, v141, v141
	v_fmac_f32_e32 v148, v142, v142
	v_fmac_f32_e32 v148, v143, v143
	v_fmac_f32_e32 v148, v144, v144
	v_fmac_f32_e32 v148, v145, v145
	v_fmac_f32_e32 v148, v146, v146
	v_fmac_f32_e32 v148, v147, v147
	v_mad_i64_i32 v[152:153], vcc, s41, v221, v[58:59]
	s_add_u32 s41, s41, 1
	global_load_dwordx4 v[6:9], v[152:153], off offset:1536
	global_load_dwordx4 v[22:25], v[152:153], off offset:2560
	s_nop 1
	v_add_f32_dpp v148, v148, v148 quad_perm:[1,0,3,2] row_mask:0xf bank_mask:0xf
	s_nop 1
	v_add_f32_dpp v148, v148, v148 quad_perm:[2,3,0,1] row_mask:0xf bank_mask:0xf
	s_nop 1
	v_add_f32_dpp v148, v148, v148 row_half_mirror row_mask:0xf bank_mask:0xf
	s_nop 1
	v_add_f32_dpp v148, v148, v148 row_mirror row_mask:0xf bank_mask:0xf
	s_nop 1
	v_add_f32_dpp v148, v148, v148 row_bcast:15 row_mask:0xa bank_mask:0xf
	s_nop 1
	v_add_f32_dpp v148, v148, v148 row_bcast:31 row_mask:0xc bank_mask:0xf
	s_nop 0
	v_readlane_b32 s0, v148, 63
	s_nop 1
	v_mov_b32_e32 v148, s0
	v_fmamk_f32 v148, v148, 0x3b000000, v162
	v_mul_f32_e32 v150, 0x4b800000, v148
	v_cmp_gt_f32_e32 vcc, s31, v148
	s_nop 1
	v_cndmask_b32_e32 v148, v148, v150, vcc
	v_rsq_f32_e32 v148, v148
	s_nop 0
	v_mul_f32_e32 v150, 0x45800000, v148
	v_cndmask_b32_e32 v149, v148, v150, vcc
	v_mul_f32_e32 v140, v149, v140
	v_mul_f32_e32 v141, v149, v141
	v_mul_f32_e32 v142, v149, v142
	v_mul_f32_e32 v143, v149, v143
	v_mul_f32_e32 v144, v149, v144
	v_mul_f32_e32 v145, v149, v145
	v_mul_f32_e32 v146, v149, v146
	v_mul_f32_e32 v147, v149, v147
	v_cvt_pk_bf16_f32 v140, v140, v141
	v_cvt_pk_bf16_f32 v141, v142, v143
	v_cvt_pk_bf16_f32 v142, v144, v145
	v_cvt_pk_bf16_f32 v143, v146, v147
	global_store_dwordx4 v[156:157], v[140:143], off offset:2048
	v_lshl_add_u64 v[156:157], v[156:157], 0, s[20:21]
	s_waitcnt vmcnt(10)
	v_lshlrev_b32_e32 v196, 16, v26
	v_and_b32_e32 v197, 0xffff0000, v26
	v_lshlrev_b32_e32 v198, 16, v27
	v_and_b32_e32 v199, 0xffff0000, v27
	v_lshlrev_b32_e32 v200, 16, v28
	v_and_b32_e32 v201, 0xffff0000, v28
	v_lshlrev_b32_e32 v202, 16, v29
	v_and_b32_e32 v203, 0xffff0000, v29
	v_mul_f32_e32 v140, v164, v196
	v_mul_f32_e32 v141, v165, v197
	v_mul_f32_e32 v142, v166, v198
	v_mul_f32_e32 v143, v167, v199
	v_mul_f32_e32 v144, v168, v200
	v_mul_f32_e32 v145, v169, v201
	v_mul_f32_e32 v146, v170, v202
	v_mul_f32_e32 v147, v171, v203
	v_fmac_f32_e32 v140, v172, v188
	v_fmac_f32_e32 v141, v173, v189
	v_fmac_f32_e32 v142, v174, v190
	v_fmac_f32_e32 v143, v175, v191
	v_fmac_f32_e32 v144, v176, v192
	v_fmac_f32_e32 v145, v177, v193
	v_fmac_f32_e32 v146, v178, v194
	v_fmac_f32_e32 v147, v179, v195
	v_fmac_f32_e32 v140, v180, v204
	v_fmac_f32_e32 v141, v181, v205
	v_fmac_f32_e32 v142, v182, v206
	v_fmac_f32_e32 v143, v183, v207
	v_fmac_f32_e32 v144, v184, v208
	v_fmac_f32_e32 v145, v185, v209
	v_fmac_f32_e32 v146, v186, v210
	v_fmac_f32_e32 v147, v187, v211
	v_lshlrev_b32_e32 v150, 16, v10
	v_and_b32_e32 v151, 0xffff0000, v10
	v_mul_f32_e32 v140, v150, v140
	v_mul_f32_e32 v141, v151, v141
	v_lshlrev_b32_e32 v150, 16, v11
	v_and_b32_e32 v151, 0xffff0000, v11
	v_mul_f32_e32 v142, v150, v142
	v_mul_f32_e32 v143, v151, v143
	v_lshlrev_b32_e32 v150, 16, v12
	v_and_b32_e32 v151, 0xffff0000, v12
	v_mul_f32_e32 v144, v150, v144
	v_mul_f32_e32 v145, v151, v145
	v_lshlrev_b32_e32 v150, 16, v13
	v_and_b32_e32 v151, 0xffff0000, v13
	v_mul_f32_e32 v146, v150, v146
	v_mul_f32_e32 v147, v151, v147
	v_mul_f32_e32 v148, v140, v140
	v_fmac_f32_e32 v148, v141, v141
	v_fmac_f32_e32 v148, v142, v142
	v_fmac_f32_e32 v148, v143, v143
	v_fmac_f32_e32 v148, v144, v144
	v_fmac_f32_e32 v148, v145, v145
	v_fmac_f32_e32 v148, v146, v146
	v_fmac_f32_e32 v148, v147, v147
	v_mad_i64_i32 v[152:153], vcc, s41, v221, v[58:59]
	s_add_u32 s41, s41, 1
	global_load_dwordx4 v[10:13], v[152:153], off offset:1536
	global_load_dwordx4 v[26:29], v[152:153], off offset:2560
	s_nop 1
	v_add_f32_dpp v148, v148, v148 quad_perm:[1,0,3,2] row_mask:0xf bank_mask:0xf
	s_nop 1
	v_add_f32_dpp v148, v148, v148 quad_perm:[2,3,0,1] row_mask:0xf bank_mask:0xf
	s_nop 1
	v_add_f32_dpp v148, v148, v148 row_half_mirror row_mask:0xf bank_mask:0xf
	s_nop 1
	v_add_f32_dpp v148, v148, v148 row_mirror row_mask:0xf bank_mask:0xf
	s_nop 1
	v_add_f32_dpp v148, v148, v148 row_bcast:15 row_mask:0xa bank_mask:0xf
	s_nop 1
	v_add_f32_dpp v148, v148, v148 row_bcast:31 row_mask:0xc bank_mask:0xf
	s_nop 0
	v_readlane_b32 s0, v148, 63
	s_nop 1
	v_mov_b32_e32 v148, s0
	v_fmamk_f32 v148, v148, 0x3b000000, v162
	v_mul_f32_e32 v150, 0x4b800000, v148
	v_cmp_gt_f32_e32 vcc, s31, v148
	s_nop 1
	v_cndmask_b32_e32 v148, v148, v150, vcc
	v_rsq_f32_e32 v148, v148
	s_nop 0
	v_mul_f32_e32 v150, 0x45800000, v148
	v_cndmask_b32_e32 v149, v148, v150, vcc
	v_mul_f32_e32 v140, v149, v140
	v_mul_f32_e32 v141, v149, v141
	v_mul_f32_e32 v142, v149, v142
	v_mul_f32_e32 v143, v149, v143
	v_mul_f32_e32 v144, v149, v144
	v_mul_f32_e32 v145, v149, v145
	v_mul_f32_e32 v146, v149, v146
	v_mul_f32_e32 v147, v149, v147
	v_cvt_pk_bf16_f32 v140, v140, v141
	v_cvt_pk_bf16_f32 v141, v142, v143
	v_cvt_pk_bf16_f32 v142, v144, v145
	v_cvt_pk_bf16_f32 v143, v146, v147
	global_store_dwordx4 v[156:157], v[140:143], off
	s_waitcnt vmcnt(10)
; __device__ __forceinline__ unsigned cvt_pk_bf16(float lo, float hi) { unsigned r; asm volatile("v_cvt_pk_bf16_f32 %0, %1, %2" : "=v"(r) : "v"(lo), "v"(hi)); return r; }
; __device__ __forceinline__ float bf_lo(unsigned w) { return __uint_as_float(w << 16); }
; __device__ __forceinline__ float bf_hi(unsigned w) { return __uint_as_float(w & 0xffff0000u); }
; __global__ void __launch_bounds__(512, 2) trunk_fwd(Args args) {
;     ...
;                 for (int rr = 0; rr < 16; ++rr) {
;                     const int r = r0 + rr;
;                     const u32x4 gb = gb_n, gu = gu_n; const f32x4 pv4 = pv_n;
;                     if (rr < 15) { gb_n = *(const u32x4*)(Z + (size_t)(r + 1) * INP + 768 + c0); gu_n = *(const u32x4*)(Z + (size_t)(r + 1) * INP + 1280 + c0);
;                                    pv_n = *(const f32x4*)(pl + (size_t)(r + 1) * PLE + lane * 4); }
;                     float cv[8], uu[8]; float ss = 0.f;
; #pragma unroll
;                     for (int i = 0; i < 4; ++i) {
;                         uu[2 * i] = bf_lo(gu[i]); uu[2 * i + 1] = bf_hi(gu[i]);
;                         cv[2 * i] = bf_lo(gb[i]) * (w0[2 * i] * uu[2 * i] + w1[2 * i] * u1[2 * i] + w2[2 * i] * u2[2 * i]);
;                         cv[2 * i + 1] = bf_hi(gb[i]) * (w0[2 * i + 1] * uu[2 * i + 1] + w1[2 * i + 1] * u1[2 * i + 1] + w2[2 * i + 1] * u2[2 * i + 1]);
;                     }
; #pragma unroll
;                     for (int i = 0; i < 8; ++i) { ss += cv[i] * cv[i]; u2[i] = u1[i]; u1[i] = uu[i]; }
;                     ss = wave_sum(ss);
;                     const float rc = rsqrtf(ss * (1.0f / 512.0f) + EPS);
;                     u32x4 oc;
; #pragma unroll
;                     for (int i = 0; i < 4; ++i) oc[i] = cvt_pk_bf16(cv[2 * i] * rc, cv[2 * i + 1] * rc);
;                     *(u32x4*)(MIX + (size_t)r * 1024 + 512 + c0) = oc;
	v_lshlrev_b32_e32 v204, 16, v30
	v_and_b32_e32 v205, 0xffff0000, v30
	v_lshlrev_b32_e32 v206, 16, v31
	v_and_b32_e32 v207, 0xffff0000, v31
	v_lshlrev_b32_e32 v208, 16, v32
	v_and_b32_e32 v209, 0xffff0000, v32
	v_lshlrev_b32_e32 v210, 16, v33
	v_and_b32_e32 v211, 0xffff0000, v33
	v_mul_f32_e32 v140, v164, v204
	v_mul_f32_e32 v141, v165, v205
	v_mul_f32_e32 v142, v166, v206
	v_mul_f32_e32 v143, v167, v207
	v_mul_f32_e32 v144, v168, v208
	v_mul_f32_e32 v145, v169, v209
	v_mul_f32_e32 v146, v170, v210
	v_mul_f32_e32 v147, v171, v211
	v_fmac_f32_e32 v140, v172, v196
	v_fmac_f32_e32 v141, v173, v197
	v_fmac_f32_e32 v142, v174, v198
	v_fmac_f32_e32 v143, v175, v199
	v_fmac_f32_e32 v144, v176, v200
	v_fmac_f32_e32 v145, v177, v201
	v_fmac_f32_e32 v146, v178, v202
	v_fmac_f32_e32 v147, v179, v203
	v_fmac_f32_e32 v140, v180, v188
	v_fmac_f32_e32 v141, v181, v189
	v_fmac_f32_e32 v142, v182, v190
	v_fmac_f32_e32 v143, v183, v191
	v_fmac_f32_e32 v144, v184, v192
	v_fmac_f32_e32 v145, v185, v193
	v_fmac_f32_e32 v146, v186, v194
	v_fmac_f32_e32 v147, v187, v195
	v_lshlrev_b32_e32 v150, 16, v14
	v_and_b32_e32 v151, 0xffff0000, v14
	v_mul_f32_e32 v140, v150, v140
	v_mul_f32_e32 v141, v151, v141
	v_lshlrev_b32_e32 v150, 16, v15
	v_and_b32_e32 v151, 0xffff0000, v15
	v_mul_f32_e32 v142, v150, v142
	v_mul_f32_e32 v143, v151, v143
	v_lshlrev_b32_e32 v150, 16, v16
	v_and_b32_e32 v151, 0xffff0000, v16
	v_mul_f32_e32 v144, v150, v144
	v_mul_f32_e32 v145, v151, v145
	v_lshlrev_b32_e32 v150, 16, v17
	v_and_b32_e32 v151, 0xffff0000, v17
	v_mul_f32_e32 v146, v150, v146
	v_mul_f32_e32 v147, v151, v147
	v_mul_f32_e32 v148, v140, v140
	v_fmac_f32_e32 v148, v141, v141
	v_fmac_f32_e32 v148, v142, v142
	v_fmac_f32_e32 v148, v143, v143
	v_fmac_f32_e32 v148, v144, v144
	v_fmac_f32_e32 v148, v145, v145
	v_fmac_f32_e32 v148, v146, v146
	v_fmac_f32_e32 v148, v147, v147
	v_mad_i64_i32 v[152:153], vcc, s41, v221, v[58:59]
	s_add_u32 s41, s41, 1
	global_load_dwordx4 v[14:17], v[152:153], off offset:1536
	global_load_dwordx4 v[30:33], v[152:153], off offset:2560
	s_nop 1
	v_add_f32_dpp v148, v148, v148 quad_perm:[1,0,3,2] row_mask:0xf bank_mask:0xf
	s_nop 1
	v_add_f32_dpp v148, v148, v148 quad_perm:[2,3,0,1] row_mask:0xf bank_mask:0xf
	s_nop 1
	v_add_f32_dpp v148, v148, v148 row_half_mirror row_mask:0xf bank_mask:0xf
	s_nop 1
	v_add_f32_dpp v148, v148, v148 row_mirror row_mask:0xf bank_mask:0xf
	s_nop 1
	v_add_f32_dpp v148, v148, v148 row_bcast:15 row_mask:0xa bank_mask:0xf
	s_nop 1
	v_add_f32_dpp v148, v148, v148 row_bcast:31 row_mask:0xc bank_mask:0xf
	s_nop 0
	v_readlane_b32 s0, v148, 63
	s_nop 1
	v_mov_b32_e32 v148, s0
	v_fmamk_f32 v148, v148, 0x3b000000, v162
	v_mul_f32_e32 v150, 0x4b800000, v148
	v_cmp_gt_f32_e32 vcc, s31, v148
	s_nop 1
	v_cndmask_b32_e32 v148, v148, v150, vcc
	v_rsq_f32_e32 v148, v148
	s_nop 0
	v_mul_f32_e32 v150, 0x45800000, v148
	v_cndmask_b32_e32 v149, v148, v150, vcc
	v_mul_f32_e32 v140, v149, v140
	v_mul_f32_e32 v141, v149, v141
	v_mul_f32_e32 v142, v149, v142
	v_mul_f32_e32 v143, v149, v143
	v_mul_f32_e32 v144, v149, v144
	v_mul_f32_e32 v145, v149, v145
	v_mul_f32_e32 v146, v149, v146
	v_mul_f32_e32 v147, v149, v147
	v_cvt_pk_bf16_f32 v140, v140, v141
	v_cvt_pk_bf16_f32 v141, v142, v143
	v_cvt_pk_bf16_f32 v142, v144, v145
	v_cvt_pk_bf16_f32 v143, v146, v147
	global_store_dwordx4 v[156:157], v[140:143], off offset:2048
	v_lshl_add_u64 v[156:157], v[156:157], 0, s[20:21]
	s_waitcnt vmcnt(10)
	v_lshlrev_b32_e32 v188, 16, v18
	v_and_b32_e32 v189, 0xffff0000, v18
	v_lshlrev_b32_e32 v190, 16, v19
	v_and_b32_e32 v191, 0xffff0000, v19
	v_lshlrev_b32_e32 v192, 16, v20
	v_and_b32_e32 v193, 0xffff0000, v20
	v_lshlrev_b32_e32 v194, 16, v21
	v_and_b32_e32 v195, 0xffff0000, v21
	v_mul_f32_e32 v140, v164, v188
	v_mul_f32_e32 v141, v165, v189
	v_mul_f32_e32 v142, v166, v190
	v_mul_f32_e32 v143, v167, v191
	v_mul_f32_e32 v144, v168, v192
	v_mul_f32_e32 v145, v169, v193
	v_mul_f32_e32 v146, v170, v194
	v_mul_f32_e32 v147, v171, v195
	v_fmac_f32_e32 v140, v172, v204
	v_fmac_f32_e32 v141, v173, v205
	v_fmac_f32_e32 v142, v174, v206
	v_fmac_f32_e32 v143, v175, v207
	v_fmac_f32_e32 v144, v176, v208
	v_fmac_f32_e32 v145, v177, v209
	v_fmac_f32_e32 v146, v178, v210
	v_fmac_f32_e32 v147, v179, v211
	v_fmac_f32_e32 v140, v180, v196
	v_fmac_f32_e32 v141, v181, v197
	v_fmac_f32_e32 v142, v182, v198
	v_fmac_f32_e32 v143, v183, v199
	v_fmac_f32_e32 v144, v184, v200
	v_fmac_f32_e32 v145, v185, v201
	v_fmac_f32_e32 v146, v186, v202
	v_fmac_f32_e32 v147, v187, v203
	v_lshlrev_b32_e32 v150, 16, v2
	v_and_b32_e32 v151, 0xffff0000, v2
	v_mul_f32_e32 v140, v150, v140
	v_mul_f32_e32 v141, v151, v141
	v_lshlrev_b32_e32 v150, 16, v3
	v_and_b32_e32 v151, 0xffff0000, v3
	v_mul_f32_e32 v142, v150, v142
	v_mul_f32_e32 v143, v151, v143
	v_lshlrev_b32_e32 v150, 16, v4
	v_and_b32_e32 v151, 0xffff0000, v4
	v_mul_f32_e32 v144, v150, v144
	v_mul_f32_e32 v145, v151, v145
	v_lshlrev_b32_e32 v150, 16, v5
	v_and_b32_e32 v151, 0xffff0000, v5
	v_mul_f32_e32 v146, v150, v146
	v_mul_f32_e32 v147, v151, v147
	v_mul_f32_e32 v148, v140, v140
	v_fmac_f32_e32 v148, v141, v141
	v_fmac_f32_e32 v148, v142, v142
	v_fmac_f32_e32 v148, v143, v143
	v_fmac_f32_e32 v148, v144, v144
	v_fmac_f32_e32 v148, v145, v145
	v_fmac_f32_e32 v148, v146, v146
	v_fmac_f32_e32 v148, v147, v147
	s_nop 1
	v_add_f32_dpp v148, v148, v148 quad_perm:[1,0,3,2] row_mask:0xf bank_mask:0xf
	s_nop 1
	v_add_f32_dpp v148, v148, v148 quad_perm:[2,3,0,1] row_mask:0xf bank_mask:0xf
	s_nop 1
	v_add_f32_dpp v148, v148, v148 row_half_mirror row_mask:0xf bank_mask:0xf
	s_nop 1
	v_add_f32_dpp v148, v148, v148 row_mirror row_mask:0xf bank_mask:0xf
	s_nop 1
	v_add_f32_dpp v148, v148, v148 row_bcast:15 row_mask:0xa bank_mask:0xf
	s_nop 1
	v_add_f32_dpp v148, v148, v148 row_bcast:31 row_mask:0xc bank_mask:0xf
	s_nop 0
	v_readlane_b32 s0, v148, 63
	s_nop 1
	v_mov_b32_e32 v148, s0
	v_fmamk_f32 v148, v148, 0x3b000000, v162
	v_mul_f32_e32 v150, 0x4b800000, v148
	v_cmp_gt_f32_e32 vcc, s31, v148
	s_nop 1
	v_cndmask_b32_e32 v148, v148, v150, vcc
	v_rsq_f32_e32 v148, v148
	s_nop 0
	v_mul_f32_e32 v150, 0x45800000, v148
	v_cndmask_b32_e32 v149, v148, v150, vcc
	v_mul_f32_e32 v140, v149, v140
	v_mul_f32_e32 v141, v149, v141
	v_mul_f32_e32 v142, v149, v142
	v_mul_f32_e32 v143, v149, v143
	v_mul_f32_e32 v144, v149, v144
	v_mul_f32_e32 v145, v149, v145
	v_mul_f32_e32 v146, v149, v146
	v_mul_f32_e32 v147, v149, v147
	v_cvt_pk_bf16_f32 v140, v140, v141
	v_cvt_pk_bf16_f32 v141, v142, v143
	v_cvt_pk_bf16_f32 v142, v144, v145
	v_cvt_pk_bf16_f32 v143, v146, v147
	global_store_dwordx4 v[156:157], v[140:143], off
	s_waitcnt vmcnt(8)
; __device__ __forceinline__ unsigned cvt_pk_bf16(float lo, float hi) { unsigned r; asm volatile("v_cvt_pk_bf16_f32 %0, %1, %2" : "=v"(r) : "v"(lo), "v"(hi)); return r; }
; __device__ __forceinline__ float bf_lo(unsigned w) { return __uint_as_float(w << 16); }
; __device__ __forceinline__ float bf_hi(unsigned w) { return __uint_as_float(w & 0xffff0000u); }
; __global__ void __launch_bounds__(512, 2) trunk_fwd(Args args) {
;     ...
;                 for (int rr = 0; rr < 16; ++rr) {
;                     const int r = r0 + rr;
;                     const u32x4 gb = gb_n, gu = gu_n; const f32x4 pv4 = pv_n;
;                     if (rr < 15) { gb_n = *(const u32x4*)(Z + (size_t)(r + 1) * INP + 768 + c0); gu_n = *(const u32x4*)(Z + (size_t)(r + 1) * INP + 1280 + c0);
;                                    pv_n = *(const f32x4*)(pl + (size_t)(r + 1) * PLE + lane * 4); }
;                     float cv[8], uu[8]; float ss = 0.f;
; #pragma unroll
;                     for (int i = 0; i < 4; ++i) {
;                         uu[2 * i] = bf_lo(gu[i]); uu[2 * i + 1] = bf_hi(gu[i]);
;                         cv[2 * i] = bf_lo(gb[i]) * (w0[2 * i] * uu[2 * i] + w1[2 * i] * u1[2 * i] + w2[2 * i] * u2[2 * i]);
;                         cv[2 * i + 1] = bf_hi(gb[i]) * (w0[2 * i + 1] * uu[2 * i + 1] + w1[2 * i + 1] * u1[2 * i + 1] + w2[2 * i + 1] * u2[2 * i + 1]);
;                     }
; #pragma unroll
;                     for (int i = 0; i < 8; ++i) { ss += cv[i] * cv[i]; u2[i] = u1[i]; u1[i] = uu[i]; }
;                     ss = wave_sum(ss);
;                     const float rc = rsqrtf(ss * (1.0f / 512.0f) + EPS);
;                     u32x4 oc;
; #pragma unroll
;                     for (int i = 0; i < 4; ++i) oc[i] = cvt_pk_bf16(cv[2 * i] * rc, cv[2 * i + 1] * rc);
;                     *(u32x4*)(MIX + (size_t)r * 1024 + 512 + c0) = oc;
	v_lshlrev_b32_e32 v196, 16, v22
	v_and_b32_e32 v197, 0xffff0000, v22
	v_lshlrev_b32_e32 v198, 16, v23
	v_and_b32_e32 v199, 0xffff0000, v23
	v_lshlrev_b32_e32 v200, 16, v24
	v_and_b32_e32 v201, 0xffff0000, v24
	v_lshlrev_b32_e32 v202, 16, v25
	v_and_b32_e32 v203, 0xffff0000, v25
	v_mul_f32_e32 v140, v164, v196
	v_mul_f32_e32 v141, v165, v197
	v_mul_f32_e32 v142, v166, v198
	v_mul_f32_e32 v143, v167, v199
	v_mul_f32_e32 v144, v168, v200
	v_mul_f32_e32 v145, v169, v201
	v_mul_f32_e32 v146, v170, v202
	v_mul_f32_e32 v147, v171, v203
	v_fmac_f32_e32 v140, v172, v188
	v_fmac_f32_e32 v141, v173, v189
	v_fmac_f32_e32 v142, v174, v190
	v_fmac_f32_e32 v143, v175, v191
	v_fmac_f32_e32 v144, v176, v192
	v_fmac_f32_e32 v145, v177, v193
	v_fmac_f32_e32 v146, v178, v194
	v_fmac_f32_e32 v147, v179, v195
	v_fmac_f32_e32 v140, v180, v204
	v_fmac_f32_e32 v141, v181, v205
	v_fmac_f32_e32 v142, v182, v206
	v_fmac_f32_e32 v143, v183, v207
	v_fmac_f32_e32 v144, v184, v208
	v_fmac_f32_e32 v145, v185, v209
	v_fmac_f32_e32 v146, v186, v210
	v_fmac_f32_e32 v147, v187, v211
	v_lshlrev_b32_e32 v150, 16, v6
	v_and_b32_e32 v151, 0xffff0000, v6
	v_mul_f32_e32 v140, v150, v140
	v_mul_f32_e32 v141, v151, v141
	v_lshlrev_b32_e32 v150, 16, v7
	v_and_b32_e32 v151, 0xffff0000, v7
	v_mul_f32_e32 v142, v150, v142
	v_mul_f32_e32 v143, v151, v143
	v_lshlrev_b32_e32 v150, 16, v8
	v_and_b32_e32 v151, 0xffff0000, v8
	v_mul_f32_e32 v144, v150, v144
	v_mul_f32_e32 v145, v151, v145
	v_lshlrev_b32_e32 v150, 16, v9
	v_and_b32_e32 v151, 0xffff0000, v9
	v_mul_f32_e32 v146, v150, v146
	v_mul_f32_e32 v147, v151, v147
	v_mul_f32_e32 v148, v140, v140
	v_fmac_f32_e32 v148, v141, v141
	v_fmac_f32_e32 v148, v142, v142
	v_fmac_f32_e32 v148, v143, v143
	v_fmac_f32_e32 v148, v144, v144
	v_fmac_f32_e32 v148, v145, v145
	v_fmac_f32_e32 v148, v146, v146
	v_fmac_f32_e32 v148, v147, v147
	s_nop 1
	v_add_f32_dpp v148, v148, v148 quad_perm:[1,0,3,2] row_mask:0xf bank_mask:0xf
	s_nop 1
	v_add_f32_dpp v148, v148, v148 quad_perm:[2,3,0,1] row_mask:0xf bank_mask:0xf
	s_nop 1
	v_add_f32_dpp v148, v148, v148 row_half_mirror row_mask:0xf bank_mask:0xf
	s_nop 1
	v_add_f32_dpp v148, v148, v148 row_mirror row_mask:0xf bank_mask:0xf
	s_nop 1
	v_add_f32_dpp v148, v148, v148 row_bcast:15 row_mask:0xa bank_mask:0xf
	s_nop 1
	v_add_f32_dpp v148, v148, v148 row_bcast:31 row_mask:0xc bank_mask:0xf
	s_nop 0
	v_readlane_b32 s0, v148, 63
	s_nop 1
	v_mov_b32_e32 v148, s0
	v_fmamk_f32 v148, v148, 0x3b000000, v162
	v_mul_f32_e32 v150, 0x4b800000, v148
	v_cmp_gt_f32_e32 vcc, s31, v148
	s_nop 1
	v_cndmask_b32_e32 v148, v148, v150, vcc
	v_rsq_f32_e32 v148, v148
	s_nop 0
	v_mul_f32_e32 v150, 0x45800000, v148
	v_cndmask_b32_e32 v149, v148, v150, vcc
	v_mul_f32_e32 v140, v149, v140
	v_mul_f32_e32 v141, v149, v141
	v_mul_f32_e32 v142, v149, v142
	v_mul_f32_e32 v143, v149, v143
	v_mul_f32_e32 v144, v149, v144
	v_mul_f32_e32 v145, v149, v145
	v_mul_f32_e32 v146, v149, v146
	v_mul_f32_e32 v147, v149, v147
	v_cvt_pk_bf16_f32 v140, v140, v141
	v_cvt_pk_bf16_f32 v141, v142, v143
	v_cvt_pk_bf16_f32 v142, v144, v145
	v_cvt_pk_bf16_f32 v143, v146, v147
	global_store_dwordx4 v[156:157], v[140:143], off offset:2048
	v_lshl_add_u64 v[156:157], v[156:157], 0, s[20:21]
	s_waitcnt vmcnt(6)
	v_lshlrev_b32_e32 v204, 16, v26
	v_and_b32_e32 v205, 0xffff0000, v26
	v_lshlrev_b32_e32 v206, 16, v27
	v_and_b32_e32 v207, 0xffff0000, v27
	v_lshlrev_b32_e32 v208, 16, v28
	v_and_b32_e32 v209, 0xffff0000, v28
	v_lshlrev_b32_e32 v210, 16, v29
	v_and_b32_e32 v211, 0xffff0000, v29
	v_mul_f32_e32 v140, v164, v204
	v_mul_f32_e32 v141, v165, v205
	v_mul_f32_e32 v142, v166, v206
	v_mul_f32_e32 v143, v167, v207
	v_mul_f32_e32 v144, v168, v208
	v_mul_f32_e32 v145, v169, v209
	v_mul_f32_e32 v146, v170, v210
	v_mul_f32_e32 v147, v171, v211
	v_fmac_f32_e32 v140, v172, v196
	v_fmac_f32_e32 v141, v173, v197
	v_fmac_f32_e32 v142, v174, v198
	v_fmac_f32_e32 v143, v175, v199
	v_fmac_f32_e32 v144, v176, v200
	v_fmac_f32_e32 v145, v177, v201
	v_fmac_f32_e32 v146, v178, v202
	v_fmac_f32_e32 v147, v179, v203
	v_fmac_f32_e32 v140, v180, v188
	v_fmac_f32_e32 v141, v181, v189
	v_fmac_f32_e32 v142, v182, v190
	v_fmac_f32_e32 v143, v183, v191
	v_fmac_f32_e32 v144, v184, v192
	v_fmac_f32_e32 v145, v185, v193
	v_fmac_f32_e32 v146, v186, v194
	v_fmac_f32_e32 v147, v187, v195
	v_lshlrev_b32_e32 v150, 16, v10
	v_and_b32_e32 v151, 0xffff0000, v10
	v_mul_f32_e32 v140, v150, v140
	v_mul_f32_e32 v141, v151, v141
	v_lshlrev_b32_e32 v150, 16, v11
	v_and_b32_e32 v151, 0xffff0000, v11
	v_mul_f32_e32 v142, v150, v142
	v_mul_f32_e32 v143, v151, v143
	v_lshlrev_b32_e32 v150, 16, v12
	v_and_b32_e32 v151, 0xffff0000, v12
	v_mul_f32_e32 v144, v150, v144
	v_mul_f32_e32 v145, v151, v145
	v_lshlrev_b32_e32 v150, 16, v13
	v_and_b32_e32 v151, 0xffff0000, v13
	v_mul_f32_e32 v146, v150, v146
	v_mul_f32_e32 v147, v151, v147
	v_mul_f32_e32 v148, v140, v140
	v_fmac_f32_e32 v148, v141, v141
	v_fmac_f32_e32 v148, v142, v142
	v_fmac_f32_e32 v148, v143, v143
	v_fmac_f32_e32 v148, v144, v144
	v_fmac_f32_e32 v148, v145, v145
	v_fmac_f32_e32 v148, v146, v146
	v_fmac_f32_e32 v148, v147, v147
	s_nop 1
	v_add_f32_dpp v148, v148, v148 quad_perm:[1,0,3,2] row_mask:0xf bank_mask:0xf
	s_nop 1
	v_add_f32_dpp v148, v148, v148 quad_perm:[2,3,0,1] row_mask:0xf bank_mask:0xf
	s_nop 1
	v_add_f32_dpp v148, v148, v148 row_half_mirror row_mask:0xf bank_mask:0xf
	s_nop 1
	v_add_f32_dpp v148, v148, v148 row_mirror row_mask:0xf bank_mask:0xf
	s_nop 1
	v_add_f32_dpp v148, v148, v148 row_bcast:15 row_mask:0xa bank_mask:0xf
	s_nop 1
	v_add_f32_dpp v148, v148, v148 row_bcast:31 row_mask:0xc bank_mask:0xf
	s_nop 0
	v_readlane_b32 s0, v148, 63
	s_nop 1
	v_mov_b32_e32 v148, s0
	v_fmamk_f32 v148, v148, 0x3b000000, v162
	v_mul_f32_e32 v150, 0x4b800000, v148
	v_cmp_gt_f32_e32 vcc, s31, v148
	s_nop 1
	v_cndmask_b32_e32 v148, v148, v150, vcc
	v_rsq_f32_e32 v148, v148
	s_nop 0
	v_mul_f32_e32 v150, 0x45800000, v148
	v_cndmask_b32_e32 v149, v148, v150, vcc
	v_mul_f32_e32 v140, v149, v140
	v_mul_f32_e32 v141, v149, v141
	v_mul_f32_e32 v142, v149, v142
	v_mul_f32_e32 v143, v149, v143
	v_mul_f32_e32 v144, v149, v144
	v_mul_f32_e32 v145, v149, v145
	v_mul_f32_e32 v146, v149, v146
	v_mul_f32_e32 v147, v149, v147
	v_cvt_pk_bf16_f32 v140, v140, v141
	v_cvt_pk_bf16_f32 v141, v142, v143
	v_cvt_pk_bf16_f32 v142, v144, v145
	v_cvt_pk_bf16_f32 v143, v146, v147
	global_store_dwordx4 v[156:157], v[140:143], off
	s_waitcnt vmcnt(4)
; __device__ __forceinline__ unsigned cvt_pk_bf16(float lo, float hi) { unsigned r; asm volatile("v_cvt_pk_bf16_f32 %0, %1, %2" : "=v"(r) : "v"(lo), "v"(hi)); return r; }
; __device__ __forceinline__ float bf_lo(unsigned w) { return __uint_as_float(w << 16); }
; __device__ __forceinline__ float bf_hi(unsigned w) { return __uint_as_float(w & 0xffff0000u); }
; __global__ void __launch_bounds__(512, 2) trunk_fwd(Args args) {
;     ...
;                 for (int rr = 0; rr < 16; ++rr) {
;                     const int r = r0 + rr;
;                     const u32x4 gb = gb_n, gu = gu_n; const f32x4 pv4 = pv_n;
;                     if (rr < 15) { gb_n = *(const u32x4*)(Z + (size_t)(r + 1) * INP + 768 + c0); gu_n = *(const u32x4*)(Z + (size_t)(r + 1) * INP + 1280 + c0);
;                                    pv_n = *(const f32x4*)(pl + (size_t)(r + 1) * PLE + lane * 4); }
;                     float cv[8], uu[8]; float ss = 0.f;
; #pragma unroll
;                     for (int i = 0; i < 4; ++i) {
;                         uu[2 * i] = bf_lo(gu[i]); uu[2 * i + 1] = bf_hi(gu[i]);
;                         cv[2 * i] = bf_lo(gb[i]) * (w0[2 * i] * uu[2 * i] + w1[2 * i] * u1[2 * i] + w2[2 * i] * u2[2 * i]);
;                         cv[2 * i + 1] = bf_hi(gb[i]) * (w0[2 * i + 1] * uu[2 * i + 1] + w1[2 * i + 1] * u1[2 * i + 1] + w2[2 * i + 1] * u2[2 * i + 1]);
;                     }
; #pragma unroll
;                     for (int i = 0; i < 8; ++i) { ss += cv[i] * cv[i]; u2[i] = u1[i]; u1[i] = uu[i]; }
;                     ss = wave_sum(ss);
;                     const float rc = rsqrtf(ss * (1.0f / 512.0f) + EPS);
;                     u32x4 oc;
; #pragma unroll
;                     for (int i = 0; i < 4; ++i) oc[i] = cvt_pk_bf16(cv[2 * i] * rc, cv[2 * i + 1] * rc);
;                     *(u32x4*)(MIX + (size_t)r * 1024 + 512 + c0) = oc;
	v_lshlrev_b32_e32 v188, 16, v30
	v_and_b32_e32 v189, 0xffff0000, v30
	v_lshlrev_b32_e32 v190, 16, v31
	v_and_b32_e32 v191, 0xffff0000, v31
	v_lshlrev_b32_e32 v192, 16, v32
	v_and_b32_e32 v193, 0xffff0000, v32
	v_lshlrev_b32_e32 v194, 16, v33
	v_and_b32_e32 v195, 0xffff0000, v33
	v_mul_f32_e32 v140, v164, v188
	v_mul_f32_e32 v141, v165, v189
	v_mul_f32_e32 v142, v166, v190
	v_mul_f32_e32 v143, v167, v191
	v_mul_f32_e32 v144, v168, v192
	v_mul_f32_e32 v145, v169, v193
	v_mul_f32_e32 v146, v170, v194
	v_mul_f32_e32 v147, v171, v195
	v_fmac_f32_e32 v140, v172, v204
	v_fmac_f32_e32 v141, v173, v205
	v_fmac_f32_e32 v142, v174, v206
	v_fmac_f32_e32 v143, v175, v207
	v_fmac_f32_e32 v144, v176, v208
	v_fmac_f32_e32 v145, v177, v209
	v_fmac_f32_e32 v146, v178, v210
	v_fmac_f32_e32 v147, v179, v211
	v_fmac_f32_e32 v140, v180, v196
	v_fmac_f32_e32 v141, v181, v197
	v_fmac_f32_e32 v142, v182, v198
	v_fmac_f32_e32 v143, v183, v199
	v_fmac_f32_e32 v144, v184, v200
	v_fmac_f32_e32 v145, v185, v201
	v_fmac_f32_e32 v146, v186, v202
	v_fmac_f32_e32 v147, v187, v203
	v_lshlrev_b32_e32 v150, 16, v14
	v_and_b32_e32 v151, 0xffff0000, v14
	v_mul_f32_e32 v140, v150, v140
	v_mul_f32_e32 v141, v151, v141
	v_lshlrev_b32_e32 v150, 16, v15
	v_and_b32_e32 v151, 0xffff0000, v15
	v_mul_f32_e32 v142, v150, v142
	v_mul_f32_e32 v143, v151, v143
	v_lshlrev_b32_e32 v150, 16, v16
	v_and_b32_e32 v151, 0xffff0000, v16
	v_mul_f32_e32 v144, v150, v144
	v_mul_f32_e32 v145, v151, v145
	v_lshlrev_b32_e32 v150, 16, v17
	v_and_b32_e32 v151, 0xffff0000, v17
	v_mul_f32_e32 v146, v150, v146
	v_mul_f32_e32 v147, v151, v147
	v_mul_f32_e32 v148, v140, v140
	v_fmac_f32_e32 v148, v141, v141
	v_fmac_f32_e32 v148, v142, v142
	v_fmac_f32_e32 v148, v143, v143
	v_fmac_f32_e32 v148, v144, v144
	v_fmac_f32_e32 v148, v145, v145
	v_fmac_f32_e32 v148, v146, v146
	v_fmac_f32_e32 v148, v147, v147
	s_nop 1
	v_add_f32_dpp v148, v148, v148 quad_perm:[1,0,3,2] row_mask:0xf bank_mask:0xf
	s_nop 1
	v_add_f32_dpp v148, v148, v148 quad_perm:[2,3,0,1] row_mask:0xf bank_mask:0xf
	s_nop 1
	v_add_f32_dpp v148, v148, v148 row_half_mirror row_mask:0xf bank_mask:0xf
	s_nop 1
	v_add_f32_dpp v148, v148, v148 row_mirror row_mask:0xf bank_mask:0xf
	s_nop 1
	v_add_f32_dpp v148, v148, v148 row_bcast:15 row_mask:0xa bank_mask:0xf
	s_nop 1
	v_add_f32_dpp v148, v148, v148 row_bcast:31 row_mask:0xc bank_mask:0xf
	s_nop 0
	v_readlane_b32 s0, v148, 63
	s_nop 1
	v_mov_b32_e32 v148, s0
	v_fmamk_f32 v148, v148, 0x3b000000, v162
	v_mul_f32_e32 v150, 0x4b800000, v148
	v_cmp_gt_f32_e32 vcc, s31, v148
	s_nop 1
	v_cndmask_b32_e32 v148, v148, v150, vcc
	v_rsq_f32_e32 v148, v148
	s_nop 0
	v_mul_f32_e32 v150, 0x45800000, v148
	v_cndmask_b32_e32 v149, v148, v150, vcc
	v_mul_f32_e32 v140, v149, v140
	v_mul_f32_e32 v141, v149, v141
	v_mul_f32_e32 v142, v149, v142
	v_mul_f32_e32 v143, v149, v143
	v_mul_f32_e32 v144, v149, v144
	v_mul_f32_e32 v145, v149, v145
	v_mul_f32_e32 v146, v149, v146
	v_mul_f32_e32 v147, v149, v147
	v_cvt_pk_bf16_f32 v140, v140, v141
	v_cvt_pk_bf16_f32 v141, v142, v143
	v_cvt_pk_bf16_f32 v142, v144, v145
	v_cvt_pk_bf16_f32 v143, v146, v147
	global_store_dwordx4 v[156:157], v[140:143], off offset:2048
	v_lshl_add_u64 v[156:157], v[156:157], 0, s[20:21]
	s_branch .LBB0_1053
